# G1/G3/G4/G5 loops: the last two iterations also run in the one-barrier-per-slice form (no generic tail loop left for these GEMMs)
# speedup vs baseline: 1.0175x; 1.0002x over previous
.Lgf_G5x_top:
	s_waitcnt vmcnt(3)
	s_waitcnt lgkmcnt(0)
	s_barrier
	v_mfma_f32_16x16x32_bf16 v[102:105], v[2:5], v[26:29], v[102:105]
	v_mfma_f32_16x16x32_bf16 v[98:101], v[6:9], v[26:29], v[98:101]
	s_add_i32 s17, s8, -3
	s_and_b32 s19, s17, 2
	s_mulk_i32 s19, 0x6000
	v_add_u32_e32 v110, s19, v142
	ds_read_b128 v[106:109], v110
	v_mfma_f32_16x16x32_bf16 v[86:89], v[10:13], v[26:29], v[86:89]
	ds_read_b128 v[144:147], v110 offset:1024
	s_and_b32 s89, s8, 3
	s_mulk_i32 s89, 0x6000
	s_add_i32 s89, s89, s88
	s_mov_b32 m0, s89
	v_mfma_f32_16x16x32_bf16 v[70:73], v[14:17], v[26:29], v[70:73]
	v_mfma_f32_16x16x32_bf16 v[90:93], v[2:5], v[22:25], v[90:93]
	global_load_lds_dwordx4 v126, s[90:91]
	s_add_i32 m0, s89, 0x2000
	v_mfma_f32_16x16x32_bf16 v[78:81], v[6:9], v[22:25], v[78:81]
	global_load_lds_dwordx4 v128, s[90:91]
	s_add_i32 m0, s89, 0x4000
	v_mfma_f32_16x16x32_bf16 v[62:65], v[10:13], v[22:25], v[62:65]
	global_load_lds_dwordx4 v130, s[92:93]
	s_add_u32 s90, s90, 64
	s_addc_u32 s91, s91, 0
	s_add_u32 s92, s92, 64
	s_addc_u32 s93, s93, 0
	v_mfma_f32_16x16x32_bf16 v[50:53], v[14:17], v[22:25], v[50:53]
	s_waitcnt lgkmcnt(0)
	v_mfma_f32_16x16x32_bf16 v[74:77], v[2:5], v[106:109], v[74:77]
	s_add_i32 s26, s8, -2
	s_and_b32 s28, s26, 3
	s_mulk_i32 s28, 0x6000
	v_add_u32_e32 v127, s28, v140
	v_add_u32_e32 v143, s28, v141
	ds_read_b128 v[26:29], v143
	v_mfma_f32_16x16x32_bf16 v[58:61], v[6:9], v[106:109], v[58:61]
	ds_read_b128 v[22:25], v143 offset:1024
	v_mfma_f32_16x16x32_bf16 v[38:41], v[10:13], v[106:109], v[38:41]
	ds_read_b128 v[118:121], v127
	v_mfma_f32_16x16x32_bf16 v[30:33], v[14:17], v[106:109], v[30:33]
	ds_read_b128 v[114:117], v127 offset:1024
	ds_read_b128 v[110:113], v127 offset:2048
	ds_read_b128 v[106:109], v127 offset:3072
	v_mfma_f32_16x16x32_bf16 v[94:97], v[2:5], v[144:147], v[94:97]
	v_mfma_f32_16x16x32_bf16 v[82:85], v[6:9], v[144:147], v[82:85]
	v_mfma_f32_16x16x32_bf16 v[66:69], v[10:13], v[144:147], v[66:69]
	v_mfma_f32_16x16x32_bf16 v[34:37], v[14:17], v[144:147], v[34:37]
	s_waitcnt vmcnt(3)
	s_waitcnt lgkmcnt(0)
	s_barrier
	v_mfma_f32_16x16x32_bf16 v[102:105], v[118:121], v[26:29], v[102:105]
	v_mfma_f32_16x16x32_bf16 v[98:101], v[114:117], v[26:29], v[98:101]
	v_add_u32_e32 v132, s28, v142
	ds_read_b128 v[144:147], v132
	v_mfma_f32_16x16x32_bf16 v[86:89], v[110:113], v[26:29], v[86:89]
	ds_read_b128 v[122:125], v132 offset:1024
	s_add_i32 s89, s19, s88
	s_mov_b32 m0, s89
	v_mfma_f32_16x16x32_bf16 v[70:73], v[106:109], v[26:29], v[70:73]
	v_mfma_f32_16x16x32_bf16 v[90:93], v[118:121], v[22:25], v[90:93]
	global_load_lds_dwordx4 v126, s[90:91]
	s_add_i32 m0, s89, 0x2000
	v_mfma_f32_16x16x32_bf16 v[78:81], v[114:117], v[22:25], v[78:81]
	global_load_lds_dwordx4 v128, s[90:91]
	s_add_i32 m0, s89, 0x4000
	v_mfma_f32_16x16x32_bf16 v[62:65], v[110:113], v[22:25], v[62:65]
	global_load_lds_dwordx4 v130, s[92:93]
	s_add_u32 s90, s90, 64
	s_addc_u32 s91, s91, 0
	s_add_u32 s92, s92, 64
	s_addc_u32 s93, s93, 0
	v_mfma_f32_16x16x32_bf16 v[50:53], v[106:109], v[22:25], v[50:53]
	s_waitcnt lgkmcnt(0)
	v_mfma_f32_16x16x32_bf16 v[74:77], v[118:121], v[144:147], v[74:77]
	s_add_i32 s19, s8, -1
	s_and_b32 s19, s19, 2
	s_mulk_i32 s19, 0x6000
	v_add_u32_e32 v127, s19, v140
	v_add_u32_e32 v132, s19, v141
	ds_read_b128 v[26:29], v132
	v_mfma_f32_16x16x32_bf16 v[58:61], v[114:117], v[144:147], v[58:61]
	ds_read_b128 v[22:25], v132 offset:1024
	v_mfma_f32_16x16x32_bf16 v[38:41], v[110:113], v[144:147], v[38:41]
	ds_read_b128 v[2:5], v127
	v_mfma_f32_16x16x32_bf16 v[30:33], v[106:109], v[144:147], v[30:33]
	ds_read_b128 v[6:9], v127 offset:1024
	ds_read_b128 v[10:13], v127 offset:2048
	ds_read_b128 v[14:17], v127 offset:3072
	s_add_u32 s20, s20, 0x80
	s_addc_u32 s21, s21, 0
	s_add_i32 s8, s8, 2
	s_cmpk_gt_u32 s17, 0x55
	v_mfma_f32_16x16x32_bf16 v[94:97], v[118:121], v[122:125], v[94:97]
	v_mfma_f32_16x16x32_bf16 v[82:85], v[114:117], v[122:125], v[82:85]
	v_mfma_f32_16x16x32_bf16 v[66:69], v[110:113], v[122:125], v[66:69]
	v_mfma_f32_16x16x32_bf16 v[34:37], v[106:109], v[122:125], v[34:37]
	s_cmp_lt_u32 s8, 86
	s_cbranch_scc1 .Lgf_G5x_top
	s_waitcnt vmcnt(3)
	s_waitcnt lgkmcnt(0)
	s_barrier
	v_mfma_f32_16x16x32_bf16 v[102:105], v[2:5], v[26:29], v[102:105]
	v_mfma_f32_16x16x32_bf16 v[98:101], v[6:9], v[26:29], v[98:101]
	s_add_i32 s17, s8, -3
	s_and_b32 s19, s17, 2
	s_mulk_i32 s19, 0x6000
	v_add_u32_e32 v110, s19, v142
	ds_read_b128 v[106:109], v110
	v_mfma_f32_16x16x32_bf16 v[86:89], v[10:13], v[26:29], v[86:89]
	ds_read_b128 v[144:147], v110 offset:1024
	s_and_b32 s89, s8, 3
	s_mulk_i32 s89, 0x6000
	s_add_i32 s89, s89, s88
	s_mov_b32 m0, s89
	v_mfma_f32_16x16x32_bf16 v[70:73], v[14:17], v[26:29], v[70:73]
	v_mfma_f32_16x16x32_bf16 v[90:93], v[2:5], v[22:25], v[90:93]
	global_load_lds_dwordx4 v126, s[90:91]
	s_add_i32 m0, s89, 0x2000
	v_mfma_f32_16x16x32_bf16 v[78:81], v[6:9], v[22:25], v[78:81]
	global_load_lds_dwordx4 v128, s[90:91]
	s_add_i32 m0, s89, 0x4000
	v_mfma_f32_16x16x32_bf16 v[62:65], v[10:13], v[22:25], v[62:65]
	global_load_lds_dwordx4 v130, s[92:93]
	s_add_u32 s90, s90, 64
	s_addc_u32 s91, s91, 0
	s_add_u32 s92, s92, 64
	s_addc_u32 s93, s93, 0
	v_mfma_f32_16x16x32_bf16 v[50:53], v[14:17], v[22:25], v[50:53]
	s_waitcnt lgkmcnt(0)
	v_mfma_f32_16x16x32_bf16 v[74:77], v[2:5], v[106:109], v[74:77]
	s_add_i32 s26, s8, -2
	s_and_b32 s28, s26, 3
	s_mulk_i32 s28, 0x6000
	v_add_u32_e32 v127, s28, v140
	v_add_u32_e32 v143, s28, v141
	ds_read_b128 v[26:29], v143
	v_mfma_f32_16x16x32_bf16 v[58:61], v[6:9], v[106:109], v[58:61]
	ds_read_b128 v[22:25], v143 offset:1024
	v_mfma_f32_16x16x32_bf16 v[38:41], v[10:13], v[106:109], v[38:41]
	ds_read_b128 v[118:121], v127
	v_mfma_f32_16x16x32_bf16 v[30:33], v[14:17], v[106:109], v[30:33]
	ds_read_b128 v[114:117], v127 offset:1024
	ds_read_b128 v[110:113], v127 offset:2048
	ds_read_b128 v[106:109], v127 offset:3072
	v_mfma_f32_16x16x32_bf16 v[94:97], v[2:5], v[144:147], v[94:97]
	v_mfma_f32_16x16x32_bf16 v[82:85], v[6:9], v[144:147], v[82:85]
	v_mfma_f32_16x16x32_bf16 v[66:69], v[10:13], v[144:147], v[66:69]
	v_mfma_f32_16x16x32_bf16 v[34:37], v[14:17], v[144:147], v[34:37]
	s_waitcnt vmcnt(3)
	s_waitcnt lgkmcnt(0)
	s_barrier
	v_mfma_f32_16x16x32_bf16 v[102:105], v[118:121], v[26:29], v[102:105]
	v_mfma_f32_16x16x32_bf16 v[98:101], v[114:117], v[26:29], v[98:101]
	v_add_u32_e32 v132, s28, v142
	ds_read_b128 v[144:147], v132
	v_mfma_f32_16x16x32_bf16 v[86:89], v[110:113], v[26:29], v[86:89]
	ds_read_b128 v[122:125], v132 offset:1024
	v_mfma_f32_16x16x32_bf16 v[70:73], v[106:109], v[26:29], v[70:73]
	v_mfma_f32_16x16x32_bf16 v[90:93], v[118:121], v[22:25], v[90:93]
	v_mfma_f32_16x16x32_bf16 v[78:81], v[114:117], v[22:25], v[78:81]
	v_mfma_f32_16x16x32_bf16 v[62:65], v[110:113], v[22:25], v[62:65]
	v_mfma_f32_16x16x32_bf16 v[50:53], v[106:109], v[22:25], v[50:53]
	s_waitcnt lgkmcnt(0)
	v_mfma_f32_16x16x32_bf16 v[74:77], v[118:121], v[144:147], v[74:77]
	s_add_i32 s19, s8, -1
	s_and_b32 s19, s19, 2
	s_mulk_i32 s19, 0x6000
	v_add_u32_e32 v127, s19, v140
	v_add_u32_e32 v132, s19, v141
	ds_read_b128 v[26:29], v132
	v_mfma_f32_16x16x32_bf16 v[58:61], v[114:117], v[144:147], v[58:61]
	ds_read_b128 v[22:25], v132 offset:1024
	v_mfma_f32_16x16x32_bf16 v[38:41], v[110:113], v[144:147], v[38:41]
	ds_read_b128 v[2:5], v127
	v_mfma_f32_16x16x32_bf16 v[30:33], v[106:109], v[144:147], v[30:33]
	ds_read_b128 v[6:9], v127 offset:1024
	ds_read_b128 v[10:13], v127 offset:2048
	ds_read_b128 v[14:17], v127 offset:3072
	s_add_u32 s20, s20, 0x80
	s_addc_u32 s21, s21, 0
	s_add_i32 s8, s8, 2
	s_cmpk_gt_u32 s17, 0x55
	v_mfma_f32_16x16x32_bf16 v[94:97], v[118:121], v[122:125], v[94:97]
	v_mfma_f32_16x16x32_bf16 v[82:85], v[114:117], v[122:125], v[82:85]
	v_mfma_f32_16x16x32_bf16 v[66:69], v[110:113], v[122:125], v[66:69]
	v_mfma_f32_16x16x32_bf16 v[34:37], v[106:109], v[122:125], v[34:37]
	s_waitcnt vmcnt(0)
	s_waitcnt lgkmcnt(0)
	s_barrier
	v_mfma_f32_16x16x32_bf16 v[102:105], v[2:5], v[26:29], v[102:105]
	v_mfma_f32_16x16x32_bf16 v[98:101], v[6:9], v[26:29], v[98:101]
	s_add_i32 s17, s8, -3
	s_and_b32 s19, s17, 2
	s_mulk_i32 s19, 0x6000
	v_add_u32_e32 v110, s19, v142
	ds_read_b128 v[106:109], v110
	v_mfma_f32_16x16x32_bf16 v[86:89], v[10:13], v[26:29], v[86:89]
	ds_read_b128 v[144:147], v110 offset:1024
	v_mfma_f32_16x16x32_bf16 v[70:73], v[14:17], v[26:29], v[70:73]
	v_mfma_f32_16x16x32_bf16 v[90:93], v[2:5], v[22:25], v[90:93]
	v_mfma_f32_16x16x32_bf16 v[78:81], v[6:9], v[22:25], v[78:81]
	v_mfma_f32_16x16x32_bf16 v[62:65], v[10:13], v[22:25], v[62:65]
	v_mfma_f32_16x16x32_bf16 v[50:53], v[14:17], v[22:25], v[50:53]
	s_waitcnt lgkmcnt(0)
	v_mfma_f32_16x16x32_bf16 v[74:77], v[2:5], v[106:109], v[74:77]
	s_add_i32 s26, s8, -2
	s_and_b32 s28, s26, 3
	s_mulk_i32 s28, 0x6000
	v_add_u32_e32 v127, s28, v140
	v_add_u32_e32 v143, s28, v141
	ds_read_b128 v[26:29], v143
	v_mfma_f32_16x16x32_bf16 v[58:61], v[6:9], v[106:109], v[58:61]
	ds_read_b128 v[22:25], v143 offset:1024
	v_mfma_f32_16x16x32_bf16 v[38:41], v[10:13], v[106:109], v[38:41]
	ds_read_b128 v[118:121], v127
	v_mfma_f32_16x16x32_bf16 v[30:33], v[14:17], v[106:109], v[30:33]
	ds_read_b128 v[114:117], v127 offset:1024
	ds_read_b128 v[110:113], v127 offset:2048
	ds_read_b128 v[106:109], v127 offset:3072
	v_mfma_f32_16x16x32_bf16 v[94:97], v[2:5], v[144:147], v[94:97]
	v_mfma_f32_16x16x32_bf16 v[82:85], v[6:9], v[144:147], v[82:85]
	v_mfma_f32_16x16x32_bf16 v[66:69], v[10:13], v[144:147], v[66:69]
	v_mfma_f32_16x16x32_bf16 v[34:37], v[14:17], v[144:147], v[34:37]
	s_waitcnt vmcnt(0)
	s_waitcnt lgkmcnt(0)
	s_barrier
	v_mfma_f32_16x16x32_bf16 v[102:105], v[118:121], v[26:29], v[102:105]
	v_mfma_f32_16x16x32_bf16 v[98:101], v[114:117], v[26:29], v[98:101]
	v_add_u32_e32 v132, s28, v142
	ds_read_b128 v[144:147], v132
	v_mfma_f32_16x16x32_bf16 v[86:89], v[110:113], v[26:29], v[86:89]
	ds_read_b128 v[122:125], v132 offset:1024
	v_mfma_f32_16x16x32_bf16 v[70:73], v[106:109], v[26:29], v[70:73]
	v_mfma_f32_16x16x32_bf16 v[90:93], v[118:121], v[22:25], v[90:93]
	v_mfma_f32_16x16x32_bf16 v[78:81], v[114:117], v[22:25], v[78:81]
	v_mfma_f32_16x16x32_bf16 v[62:65], v[110:113], v[22:25], v[62:65]
	v_mfma_f32_16x16x32_bf16 v[50:53], v[106:109], v[22:25], v[50:53]
	s_waitcnt lgkmcnt(0)
	v_mfma_f32_16x16x32_bf16 v[74:77], v[118:121], v[144:147], v[74:77]
	v_mfma_f32_16x16x32_bf16 v[58:61], v[114:117], v[144:147], v[58:61]
	v_mfma_f32_16x16x32_bf16 v[38:41], v[110:113], v[144:147], v[38:41]
	v_mfma_f32_16x16x32_bf16 v[30:33], v[106:109], v[144:147], v[30:33]
	s_add_u32 s20, s20, 0x80
	s_addc_u32 s21, s21, 0
	s_add_i32 s8, s8, 2
	s_cmpk_gt_u32 s17, 0x55
	v_mfma_f32_16x16x32_bf16 v[94:97], v[118:121], v[122:125], v[94:97]
	v_mfma_f32_16x16x32_bf16 v[82:85], v[114:117], v[122:125], v[82:85]
	v_mfma_f32_16x16x32_bf16 v[66:69], v[110:113], v[122:125], v[66:69]
	v_mfma_f32_16x16x32_bf16 v[34:37], v[106:109], v[122:125], v[34:37]
	s_branch .LBB0_135

.Lgr_G5x_tail:
	s_waitcnt lgkmcnt(0)
	v_mfma_f32_16x16x32_bf16 v[102:105], v[2:5], v[26:29], v[102:105]
	v_mfma_f32_16x16x32_bf16 v[98:101], v[6:9], v[26:29], v[98:101]
	s_add_i32 s17, s8, -3
	s_and_b32 s19, s17, 2
	s_mulk_i32 s19, 0x6000
	v_add_u32_e32 v110, s19, v142
	ds_read_b128 v[106:109], v110
	v_mfma_f32_16x16x32_bf16 v[86:89], v[10:13], v[26:29], v[86:89]
	ds_read_b128 v[144:147], v110 offset:1024
	s_and_b32 s89, s8, 3
	s_mulk_i32 s89, 0x6000
	s_add_i32 s89, s89, s88
	s_mov_b32 m0, s89
	v_mfma_f32_16x16x32_bf16 v[70:73], v[14:17], v[26:29], v[70:73]
	v_mfma_f32_16x16x32_bf16 v[90:93], v[2:5], v[22:25], v[90:93]
	global_load_lds_dwordx4 v126, s[90:91]
	s_add_i32 m0, s89, 0x2000
	v_mfma_f32_16x16x32_bf16 v[78:81], v[6:9], v[22:25], v[78:81]
	global_load_lds_dwordx4 v128, s[90:91]
	s_add_i32 m0, s89, 0x4000
	v_mfma_f32_16x16x32_bf16 v[62:65], v[10:13], v[22:25], v[62:65]
	global_load_lds_dwordx4 v130, s[92:93]
	s_add_u32 s90, s90, 64
	s_addc_u32 s91, s91, 0
	s_add_u32 s92, s92, 64
	s_addc_u32 s93, s93, 0
	v_mfma_f32_16x16x32_bf16 v[50:53], v[14:17], v[22:25], v[50:53]
	s_waitcnt vmcnt(3)
	s_waitcnt lgkmcnt(0)
	s_barrier
	v_mfma_f32_16x16x32_bf16 v[74:77], v[2:5], v[106:109], v[74:77]
	s_add_i32 s26, s8, -2
	s_and_b32 s28, s26, 3
	s_mulk_i32 s28, 0x6000
	v_add_u32_e32 v127, s28, v140
	v_add_u32_e32 v143, s28, v141
	ds_read_b128 v[26:29], v143
	v_mfma_f32_16x16x32_bf16 v[58:61], v[6:9], v[106:109], v[58:61]
	ds_read_b128 v[22:25], v143 offset:1024
	v_mfma_f32_16x16x32_bf16 v[38:41], v[10:13], v[106:109], v[38:41]
	ds_read_b128 v[118:121], v127
	v_mfma_f32_16x16x32_bf16 v[30:33], v[14:17], v[106:109], v[30:33]
	ds_read_b128 v[114:117], v127 offset:1024
	ds_read_b128 v[110:113], v127 offset:2048
	ds_read_b128 v[106:109], v127 offset:3072
	v_mfma_f32_16x16x32_bf16 v[94:97], v[2:5], v[144:147], v[94:97]
	v_mfma_f32_16x16x32_bf16 v[82:85], v[6:9], v[144:147], v[82:85]
	v_mfma_f32_16x16x32_bf16 v[66:69], v[10:13], v[144:147], v[66:69]
	v_mfma_f32_16x16x32_bf16 v[34:37], v[14:17], v[144:147], v[34:37]
	s_waitcnt lgkmcnt(0)
	v_mfma_f32_16x16x32_bf16 v[102:105], v[118:121], v[26:29], v[102:105]
	v_mfma_f32_16x16x32_bf16 v[98:101], v[114:117], v[26:29], v[98:101]
	v_add_u32_e32 v132, s28, v142
	ds_read_b128 v[144:147], v132
	v_mfma_f32_16x16x32_bf16 v[86:89], v[110:113], v[26:29], v[86:89]
	ds_read_b128 v[122:125], v132 offset:1024
	v_mfma_f32_16x16x32_bf16 v[70:73], v[106:109], v[26:29], v[70:73]
	v_mfma_f32_16x16x32_bf16 v[90:93], v[118:121], v[22:25], v[90:93]
	v_mfma_f32_16x16x32_bf16 v[78:81], v[114:117], v[22:25], v[78:81]
	v_mfma_f32_16x16x32_bf16 v[62:65], v[110:113], v[22:25], v[62:65]
	v_mfma_f32_16x16x32_bf16 v[50:53], v[106:109], v[22:25], v[50:53]
	s_waitcnt vmcnt(0)
	s_waitcnt lgkmcnt(0)
	s_barrier
	v_mfma_f32_16x16x32_bf16 v[74:77], v[118:121], v[144:147], v[74:77]
	s_add_i32 s19, s8, -1
	s_and_b32 s19, s19, 2
	s_mulk_i32 s19, 0x6000
	v_add_u32_e32 v127, s19, v140
	v_add_u32_e32 v132, s19, v141
	ds_read_b128 v[26:29], v132
	v_mfma_f32_16x16x32_bf16 v[58:61], v[114:117], v[144:147], v[58:61]
	ds_read_b128 v[22:25], v132 offset:1024
	v_mfma_f32_16x16x32_bf16 v[38:41], v[110:113], v[144:147], v[38:41]
	ds_read_b128 v[2:5], v127
	v_mfma_f32_16x16x32_bf16 v[30:33], v[106:109], v[144:147], v[30:33]
	ds_read_b128 v[6:9], v127 offset:1024
	ds_read_b128 v[10:13], v127 offset:2048
	ds_read_b128 v[14:17], v127 offset:3072
	s_add_u32 s20, s20, 0x80
	s_addc_u32 s21, s21, 0
	s_add_i32 s8, s8, 2
	s_cmpk_gt_u32 s17, 0x55
	v_mfma_f32_16x16x32_bf16 v[94:97], v[118:121], v[122:125], v[94:97]
	v_mfma_f32_16x16x32_bf16 v[82:85], v[114:117], v[122:125], v[82:85]
	v_mfma_f32_16x16x32_bf16 v[66:69], v[110:113], v[122:125], v[66:69]
	v_mfma_f32_16x16x32_bf16 v[34:37], v[106:109], v[122:125], v[34:37]
	s_waitcnt lgkmcnt(0)
	v_mfma_f32_16x16x32_bf16 v[102:105], v[2:5], v[26:29], v[102:105]
	v_mfma_f32_16x16x32_bf16 v[98:101], v[6:9], v[26:29], v[98:101]
	s_add_i32 s17, s8, -3
	s_and_b32 s19, s17, 2
	s_mulk_i32 s19, 0x6000
	v_add_u32_e32 v110, s19, v142
	ds_read_b128 v[106:109], v110
	v_mfma_f32_16x16x32_bf16 v[86:89], v[10:13], v[26:29], v[86:89]
	ds_read_b128 v[144:147], v110 offset:1024
	v_mfma_f32_16x16x32_bf16 v[70:73], v[14:17], v[26:29], v[70:73]
	v_mfma_f32_16x16x32_bf16 v[90:93], v[2:5], v[22:25], v[90:93]
	v_mfma_f32_16x16x32_bf16 v[78:81], v[6:9], v[22:25], v[78:81]
	v_mfma_f32_16x16x32_bf16 v[62:65], v[10:13], v[22:25], v[62:65]
	v_mfma_f32_16x16x32_bf16 v[50:53], v[14:17], v[22:25], v[50:53]
	s_waitcnt vmcnt(0)
	s_waitcnt lgkmcnt(0)
	s_barrier
	v_mfma_f32_16x16x32_bf16 v[74:77], v[2:5], v[106:109], v[74:77]
	s_add_i32 s26, s8, -2
	s_and_b32 s28, s26, 3
	s_mulk_i32 s28, 0x6000
	v_add_u32_e32 v127, s28, v140
	v_add_u32_e32 v143, s28, v141
	ds_read_b128 v[26:29], v143
	v_mfma_f32_16x16x32_bf16 v[58:61], v[6:9], v[106:109], v[58:61]
	ds_read_b128 v[22:25], v143 offset:1024
	v_mfma_f32_16x16x32_bf16 v[38:41], v[10:13], v[106:109], v[38:41]
	ds_read_b128 v[118:121], v127
	v_mfma_f32_16x16x32_bf16 v[30:33], v[14:17], v[106:109], v[30:33]
	ds_read_b128 v[114:117], v127 offset:1024
	ds_read_b128 v[110:113], v127 offset:2048
	ds_read_b128 v[106:109], v127 offset:3072
	v_mfma_f32_16x16x32_bf16 v[94:97], v[2:5], v[144:147], v[94:97]
	v_mfma_f32_16x16x32_bf16 v[82:85], v[6:9], v[144:147], v[82:85]
	v_mfma_f32_16x16x32_bf16 v[66:69], v[10:13], v[144:147], v[66:69]
	v_mfma_f32_16x16x32_bf16 v[34:37], v[14:17], v[144:147], v[34:37]
	s_waitcnt lgkmcnt(0)
	v_mfma_f32_16x16x32_bf16 v[102:105], v[118:121], v[26:29], v[102:105]
	v_mfma_f32_16x16x32_bf16 v[98:101], v[114:117], v[26:29], v[98:101]
	v_add_u32_e32 v132, s28, v142
	ds_read_b128 v[144:147], v132
	v_mfma_f32_16x16x32_bf16 v[86:89], v[110:113], v[26:29], v[86:89]
	ds_read_b128 v[122:125], v132 offset:1024
	v_mfma_f32_16x16x32_bf16 v[70:73], v[106:109], v[26:29], v[70:73]
	v_mfma_f32_16x16x32_bf16 v[90:93], v[118:121], v[22:25], v[90:93]
	v_mfma_f32_16x16x32_bf16 v[78:81], v[114:117], v[22:25], v[78:81]
	v_mfma_f32_16x16x32_bf16 v[62:65], v[110:113], v[22:25], v[62:65]
	v_mfma_f32_16x16x32_bf16 v[50:53], v[106:109], v[22:25], v[50:53]
	s_waitcnt vmcnt(0)
	s_waitcnt lgkmcnt(0)
	s_barrier
	v_mfma_f32_16x16x32_bf16 v[74:77], v[118:121], v[144:147], v[74:77]
	v_mfma_f32_16x16x32_bf16 v[58:61], v[114:117], v[144:147], v[58:61]
	v_mfma_f32_16x16x32_bf16 v[38:41], v[110:113], v[144:147], v[38:41]
	v_mfma_f32_16x16x32_bf16 v[30:33], v[106:109], v[144:147], v[30:33]
	s_add_u32 s20, s20, 0x80
	s_addc_u32 s21, s21, 0
	s_add_i32 s8, s8, 2
	s_cmpk_gt_u32 s17, 0x55
	v_mfma_f32_16x16x32_bf16 v[94:97], v[118:121], v[122:125], v[94:97]
	v_mfma_f32_16x16x32_bf16 v[82:85], v[114:117], v[122:125], v[82:85]
	v_mfma_f32_16x16x32_bf16 v[66:69], v[110:113], v[122:125], v[66:69]
	v_mfma_f32_16x16x32_bf16 v[34:37], v[106:109], v[122:125], v[34:37]
	s_branch .LBB0_135

.Lgf_G4x_top:
	s_waitcnt vmcnt(4)
	s_waitcnt lgkmcnt(0)
	s_barrier
	v_mfma_f32_16x16x32_bf16 v[158:161], v[122:125], v[150:153], v[158:161]
	v_mfma_f32_16x16x32_bf16 v[94:97], v[126:129], v[150:153], v[94:97]
	s_add_i32 s28, s31, 0xfffe8000
	s_and_b32 s34, s28, 0x10000
	v_add_u32_e32 v170, s34, v230
	ds_read_b128 v[162:165], v170
	v_mfma_f32_16x16x32_bf16 v[62:65], v[130:133], v[150:153], v[62:65]
	ds_read_b128 v[166:169], v170 offset:1024
	v_mfma_f32_16x16x32_bf16 v[30:33], v[134:137], v[150:153], v[30:33]
	ds_read_b128 v[232:235], v170 offset:2048
	v_mfma_f32_16x16x32_bf16 v[118:121], v[122:125], v[146:149], v[118:121]
	ds_read_b128 v[236:239], v170 offset:3072
	s_and_b32 s89, s31, 0x18000
	s_add_i32 s89, s89, s88
	s_mov_b32 m0, s89
	v_mfma_f32_16x16x32_bf16 v[86:89], v[126:129], v[146:149], v[86:89]
	v_mfma_f32_16x16x32_bf16 v[54:57], v[130:133], v[146:149], v[54:57]
	global_load_lds_dwordx4 v186, s[90:91]
	s_add_i32 m0, s89, 0x2000
	v_mfma_f32_16x16x32_bf16 v[22:25], v[134:137], v[146:149], v[22:25]
	v_mfma_f32_16x16x32_bf16 v[110:113], v[122:125], v[142:145], v[110:113]
	v_mfma_f32_16x16x32_bf16 v[78:81], v[126:129], v[142:145], v[78:81]
	global_load_lds_dwordx4 v188, s[90:91]
	s_add_i32 m0, s89, 0x4000
	v_mfma_f32_16x16x32_bf16 v[46:49], v[130:133], v[142:145], v[46:49]
	v_mfma_f32_16x16x32_bf16 v[14:17], v[134:137], v[142:145], v[14:17]
	global_load_lds_dwordx4 v190, s[92:93]
	s_add_i32 m0, s89, 0x6000
	v_mfma_f32_16x16x32_bf16 v[102:105], v[122:125], v[138:141], v[102:105]
	v_mfma_f32_16x16x32_bf16 v[70:73], v[126:129], v[138:141], v[70:73]
	global_load_lds_dwordx4 v192, s[92:93]
	s_add_u32 s90, s90, 64
	s_addc_u32 s91, s91, 0
	s_add_u32 s92, s92, 64
	s_addc_u32 s93, s93, 0
	v_mfma_f32_16x16x32_bf16 v[38:41], v[130:133], v[138:141], v[38:41]
	v_mfma_f32_16x16x32_bf16 v[6:9], v[134:137], v[138:141], v[6:9]
	s_waitcnt lgkmcnt(0)
	v_mfma_f32_16x16x32_bf16 v[154:157], v[122:125], v[162:165], v[154:157]
	s_add_i32 s28, s31, 0xffff0000
	s_and_b32 s35, s28, 0x18000
	v_add_u32_e32 v187, s35, v200
	v_add_u32_e32 v226, s35, v201
	ds_read_b128 v[150:153], v226
	v_mfma_f32_16x16x32_bf16 v[90:93], v[126:129], v[162:165], v[90:93]
	ds_read_b128 v[146:149], v226 offset:1024
	v_mfma_f32_16x16x32_bf16 v[58:61], v[130:133], v[162:165], v[58:61]
	ds_read_b128 v[142:145], v226 offset:2048
	v_mfma_f32_16x16x32_bf16 v[26:29], v[134:137], v[162:165], v[26:29]
	ds_read_b128 v[138:141], v226 offset:3072
	v_mfma_f32_16x16x32_bf16 v[114:117], v[122:125], v[166:169], v[114:117]
	ds_read_b128 v[174:177], v187
	v_mfma_f32_16x16x32_bf16 v[82:85], v[126:129], v[166:169], v[82:85]
	ds_read_b128 v[170:173], v187 offset:1024
	v_mfma_f32_16x16x32_bf16 v[50:53], v[130:133], v[166:169], v[50:53]
	ds_read_b128 v[162:165], v187 offset:3072
	v_mfma_f32_16x16x32_bf16 v[18:21], v[134:137], v[166:169], v[18:21]
	ds_read_b128 v[166:169], v187 offset:2048
	v_mfma_f32_16x16x32_bf16 v[106:109], v[122:125], v[232:235], v[106:109]
	v_mfma_f32_16x16x32_bf16 v[74:77], v[126:129], v[232:235], v[74:77]
	v_mfma_f32_16x16x32_bf16 v[42:45], v[130:133], v[232:235], v[42:45]
	v_mfma_f32_16x16x32_bf16 v[10:13], v[134:137], v[232:235], v[10:13]
	v_mfma_f32_16x16x32_bf16 v[98:101], v[122:125], v[236:239], v[98:101]
	v_mfma_f32_16x16x32_bf16 v[66:69], v[126:129], v[236:239], v[66:69]
	v_mfma_f32_16x16x32_bf16 v[34:37], v[130:133], v[236:239], v[34:37]
	v_mfma_f32_16x16x32_bf16 v[2:5], v[134:137], v[236:239], v[2:5]
	s_waitcnt vmcnt(4)
	s_waitcnt lgkmcnt(0)
	s_barrier
	v_mfma_f32_16x16x32_bf16 v[158:161], v[174:177], v[150:153], v[158:161]
	v_mfma_f32_16x16x32_bf16 v[94:97], v[170:173], v[150:153], v[94:97]
	v_add_u32_e32 v226, s35, v230
	ds_read_b128 v[232:235], v226
	v_mfma_f32_16x16x32_bf16 v[62:65], v[166:169], v[150:153], v[62:65]
	ds_read_b128 v[236:239], v226 offset:1024
	v_mfma_f32_16x16x32_bf16 v[30:33], v[162:165], v[150:153], v[30:33]
	ds_read_b128 v[182:185], v226 offset:2048
	v_mfma_f32_16x16x32_bf16 v[118:121], v[174:177], v[146:149], v[118:121]
	ds_read_b128 v[178:181], v226 offset:3072
	s_add_i32 s89, s34, s88
	s_mov_b32 m0, s89
	v_mfma_f32_16x16x32_bf16 v[86:89], v[170:173], v[146:149], v[86:89]
	v_mfma_f32_16x16x32_bf16 v[54:57], v[166:169], v[146:149], v[54:57]
	global_load_lds_dwordx4 v186, s[90:91]
	s_add_i32 m0, s89, 0x2000
	v_mfma_f32_16x16x32_bf16 v[22:25], v[162:165], v[146:149], v[22:25]
	v_mfma_f32_16x16x32_bf16 v[110:113], v[174:177], v[142:145], v[110:113]
	v_mfma_f32_16x16x32_bf16 v[78:81], v[170:173], v[142:145], v[78:81]
	global_load_lds_dwordx4 v188, s[90:91]
	s_add_i32 m0, s89, 0x4000
	v_mfma_f32_16x16x32_bf16 v[46:49], v[166:169], v[142:145], v[46:49]
	v_mfma_f32_16x16x32_bf16 v[14:17], v[162:165], v[142:145], v[14:17]
	global_load_lds_dwordx4 v190, s[92:93]
	s_add_i32 m0, s89, 0x6000
	v_mfma_f32_16x16x32_bf16 v[102:105], v[174:177], v[138:141], v[102:105]
	v_mfma_f32_16x16x32_bf16 v[70:73], v[170:173], v[138:141], v[70:73]
	global_load_lds_dwordx4 v192, s[92:93]
	s_add_u32 s90, s90, 64
	s_addc_u32 s91, s91, 0
	s_add_u32 s92, s92, 64
	s_addc_u32 s93, s93, 0
	v_mfma_f32_16x16x32_bf16 v[38:41], v[166:169], v[138:141], v[38:41]
	v_mfma_f32_16x16x32_bf16 v[6:9], v[162:165], v[138:141], v[6:9]
	s_waitcnt lgkmcnt(0)
	v_mfma_f32_16x16x32_bf16 v[154:157], v[174:177], v[232:235], v[154:157]
	s_add_i32 s24, s31, 0xffff8000
	s_and_b32 s24, s24, 0x10000
	v_add_u32_e32 v187, s24, v200
	v_add_u32_e32 v226, s24, v201
	ds_read_b128 v[150:153], v226
	v_mfma_f32_16x16x32_bf16 v[90:93], v[170:173], v[232:235], v[90:93]
	ds_read_b128 v[146:149], v226 offset:1024
	v_mfma_f32_16x16x32_bf16 v[58:61], v[166:169], v[232:235], v[58:61]
	ds_read_b128 v[142:145], v226 offset:2048
	v_mfma_f32_16x16x32_bf16 v[26:29], v[162:165], v[232:235], v[26:29]
	ds_read_b128 v[138:141], v226 offset:3072
	v_mfma_f32_16x16x32_bf16 v[114:117], v[174:177], v[236:239], v[114:117]
	ds_read_b128 v[122:125], v187
	v_mfma_f32_16x16x32_bf16 v[82:85], v[170:173], v[236:239], v[82:85]
	ds_read_b128 v[126:129], v187 offset:1024
	v_mfma_f32_16x16x32_bf16 v[50:53], v[166:169], v[236:239], v[50:53]
	ds_read_b128 v[130:133], v187 offset:2048
	v_mfma_f32_16x16x32_bf16 v[18:21], v[162:165], v[236:239], v[18:21]
	ds_read_b128 v[134:137], v187 offset:3072
	s_add_i32 s19, s19, 2
	s_add_u32 s20, s20, 0x80
	s_addc_u32 s21, s21, 0
	s_add_i32 s31, s31, 0x10000
	v_mfma_f32_16x16x32_bf16 v[106:109], v[174:177], v[182:185], v[106:109]
	v_mfma_f32_16x16x32_bf16 v[74:77], v[170:173], v[182:185], v[74:77]
	v_mfma_f32_16x16x32_bf16 v[42:45], v[166:169], v[182:185], v[42:45]
	v_mfma_f32_16x16x32_bf16 v[10:13], v[162:165], v[182:185], v[10:13]
	v_mfma_f32_16x16x32_bf16 v[98:101], v[174:177], v[178:181], v[98:101]
	v_mfma_f32_16x16x32_bf16 v[66:69], v[170:173], v[178:181], v[66:69]
	v_mfma_f32_16x16x32_bf16 v[34:37], v[166:169], v[178:181], v[34:37]
	v_mfma_f32_16x16x32_bf16 v[2:5], v[162:165], v[178:181], v[2:5]
	s_cmp_lt_u32 s19, 28
	s_cbranch_scc1 .Lgf_G4x_top
	s_waitcnt vmcnt(4)
	s_waitcnt lgkmcnt(0)
	s_barrier
	v_mfma_f32_16x16x32_bf16 v[158:161], v[122:125], v[150:153], v[158:161]
	v_mfma_f32_16x16x32_bf16 v[94:97], v[126:129], v[150:153], v[94:97]
	s_add_i32 s28, s31, 0xfffe8000
	s_and_b32 s34, s28, 0x10000
	v_add_u32_e32 v170, s34, v230
	ds_read_b128 v[162:165], v170
	v_mfma_f32_16x16x32_bf16 v[62:65], v[130:133], v[150:153], v[62:65]
	ds_read_b128 v[166:169], v170 offset:1024
	v_mfma_f32_16x16x32_bf16 v[30:33], v[134:137], v[150:153], v[30:33]
	ds_read_b128 v[232:235], v170 offset:2048
	v_mfma_f32_16x16x32_bf16 v[118:121], v[122:125], v[146:149], v[118:121]
	ds_read_b128 v[236:239], v170 offset:3072
	s_and_b32 s89, s31, 0x18000
	s_add_i32 s89, s89, s88
	s_mov_b32 m0, s89
	v_mfma_f32_16x16x32_bf16 v[86:89], v[126:129], v[146:149], v[86:89]
	v_mfma_f32_16x16x32_bf16 v[54:57], v[130:133], v[146:149], v[54:57]
	global_load_lds_dwordx4 v186, s[90:91]
	s_add_i32 m0, s89, 0x2000
	v_mfma_f32_16x16x32_bf16 v[22:25], v[134:137], v[146:149], v[22:25]
	v_mfma_f32_16x16x32_bf16 v[110:113], v[122:125], v[142:145], v[110:113]
	v_mfma_f32_16x16x32_bf16 v[78:81], v[126:129], v[142:145], v[78:81]
	global_load_lds_dwordx4 v188, s[90:91]
	s_add_i32 m0, s89, 0x4000
	v_mfma_f32_16x16x32_bf16 v[46:49], v[130:133], v[142:145], v[46:49]
	v_mfma_f32_16x16x32_bf16 v[14:17], v[134:137], v[142:145], v[14:17]
	global_load_lds_dwordx4 v190, s[92:93]
	s_add_i32 m0, s89, 0x6000
	v_mfma_f32_16x16x32_bf16 v[102:105], v[122:125], v[138:141], v[102:105]
	v_mfma_f32_16x16x32_bf16 v[70:73], v[126:129], v[138:141], v[70:73]
	global_load_lds_dwordx4 v192, s[92:93]
	s_add_u32 s90, s90, 64
	s_addc_u32 s91, s91, 0
	s_add_u32 s92, s92, 64
	s_addc_u32 s93, s93, 0
	v_mfma_f32_16x16x32_bf16 v[38:41], v[130:133], v[138:141], v[38:41]
	v_mfma_f32_16x16x32_bf16 v[6:9], v[134:137], v[138:141], v[6:9]
	s_waitcnt lgkmcnt(0)
	v_mfma_f32_16x16x32_bf16 v[154:157], v[122:125], v[162:165], v[154:157]
	s_add_i32 s28, s31, 0xffff0000
	s_and_b32 s35, s28, 0x18000
	v_add_u32_e32 v187, s35, v200
	v_add_u32_e32 v226, s35, v201
	ds_read_b128 v[150:153], v226
	v_mfma_f32_16x16x32_bf16 v[90:93], v[126:129], v[162:165], v[90:93]
	ds_read_b128 v[146:149], v226 offset:1024
	v_mfma_f32_16x16x32_bf16 v[58:61], v[130:133], v[162:165], v[58:61]
	ds_read_b128 v[142:145], v226 offset:2048
	v_mfma_f32_16x16x32_bf16 v[26:29], v[134:137], v[162:165], v[26:29]
	ds_read_b128 v[138:141], v226 offset:3072
	v_mfma_f32_16x16x32_bf16 v[114:117], v[122:125], v[166:169], v[114:117]
	ds_read_b128 v[174:177], v187
	v_mfma_f32_16x16x32_bf16 v[82:85], v[126:129], v[166:169], v[82:85]
	ds_read_b128 v[170:173], v187 offset:1024
	v_mfma_f32_16x16x32_bf16 v[50:53], v[130:133], v[166:169], v[50:53]
	ds_read_b128 v[162:165], v187 offset:3072
	v_mfma_f32_16x16x32_bf16 v[18:21], v[134:137], v[166:169], v[18:21]
	ds_read_b128 v[166:169], v187 offset:2048
	v_mfma_f32_16x16x32_bf16 v[106:109], v[122:125], v[232:235], v[106:109]
	v_mfma_f32_16x16x32_bf16 v[74:77], v[126:129], v[232:235], v[74:77]
	v_mfma_f32_16x16x32_bf16 v[42:45], v[130:133], v[232:235], v[42:45]
	v_mfma_f32_16x16x32_bf16 v[10:13], v[134:137], v[232:235], v[10:13]
	v_mfma_f32_16x16x32_bf16 v[98:101], v[122:125], v[236:239], v[98:101]
	v_mfma_f32_16x16x32_bf16 v[66:69], v[126:129], v[236:239], v[66:69]
	v_mfma_f32_16x16x32_bf16 v[34:37], v[130:133], v[236:239], v[34:37]
	v_mfma_f32_16x16x32_bf16 v[2:5], v[134:137], v[236:239], v[2:5]
	s_waitcnt vmcnt(4)
	s_waitcnt lgkmcnt(0)
	s_barrier
	v_mfma_f32_16x16x32_bf16 v[158:161], v[174:177], v[150:153], v[158:161]
	v_mfma_f32_16x16x32_bf16 v[94:97], v[170:173], v[150:153], v[94:97]
	v_add_u32_e32 v226, s35, v230
	ds_read_b128 v[232:235], v226
	v_mfma_f32_16x16x32_bf16 v[62:65], v[166:169], v[150:153], v[62:65]
	ds_read_b128 v[236:239], v226 offset:1024
	v_mfma_f32_16x16x32_bf16 v[30:33], v[162:165], v[150:153], v[30:33]
	ds_read_b128 v[182:185], v226 offset:2048
	v_mfma_f32_16x16x32_bf16 v[118:121], v[174:177], v[146:149], v[118:121]
	ds_read_b128 v[178:181], v226 offset:3072
	v_mfma_f32_16x16x32_bf16 v[86:89], v[170:173], v[146:149], v[86:89]
	v_mfma_f32_16x16x32_bf16 v[54:57], v[166:169], v[146:149], v[54:57]
	v_mfma_f32_16x16x32_bf16 v[22:25], v[162:165], v[146:149], v[22:25]
	v_mfma_f32_16x16x32_bf16 v[110:113], v[174:177], v[142:145], v[110:113]
	v_mfma_f32_16x16x32_bf16 v[78:81], v[170:173], v[142:145], v[78:81]
	v_mfma_f32_16x16x32_bf16 v[46:49], v[166:169], v[142:145], v[46:49]
	v_mfma_f32_16x16x32_bf16 v[14:17], v[162:165], v[142:145], v[14:17]
	v_mfma_f32_16x16x32_bf16 v[102:105], v[174:177], v[138:141], v[102:105]
	v_mfma_f32_16x16x32_bf16 v[70:73], v[170:173], v[138:141], v[70:73]
	v_mfma_f32_16x16x32_bf16 v[38:41], v[166:169], v[138:141], v[38:41]
	v_mfma_f32_16x16x32_bf16 v[6:9], v[162:165], v[138:141], v[6:9]
	s_waitcnt lgkmcnt(0)
	v_mfma_f32_16x16x32_bf16 v[154:157], v[174:177], v[232:235], v[154:157]
	s_add_i32 s24, s31, 0xffff8000
	s_and_b32 s24, s24, 0x10000
	v_add_u32_e32 v187, s24, v200
	v_add_u32_e32 v226, s24, v201
	ds_read_b128 v[150:153], v226
	v_mfma_f32_16x16x32_bf16 v[90:93], v[170:173], v[232:235], v[90:93]
	ds_read_b128 v[146:149], v226 offset:1024
	v_mfma_f32_16x16x32_bf16 v[58:61], v[166:169], v[232:235], v[58:61]
	ds_read_b128 v[142:145], v226 offset:2048
	v_mfma_f32_16x16x32_bf16 v[26:29], v[162:165], v[232:235], v[26:29]
	ds_read_b128 v[138:141], v226 offset:3072
	v_mfma_f32_16x16x32_bf16 v[114:117], v[174:177], v[236:239], v[114:117]
	ds_read_b128 v[122:125], v187
	v_mfma_f32_16x16x32_bf16 v[82:85], v[170:173], v[236:239], v[82:85]
	ds_read_b128 v[126:129], v187 offset:1024
	v_mfma_f32_16x16x32_bf16 v[50:53], v[166:169], v[236:239], v[50:53]
	ds_read_b128 v[130:133], v187 offset:2048
	v_mfma_f32_16x16x32_bf16 v[18:21], v[162:165], v[236:239], v[18:21]
	ds_read_b128 v[134:137], v187 offset:3072
	s_add_i32 s19, s19, 2
	s_add_u32 s20, s20, 0x80
	s_addc_u32 s21, s21, 0
	s_add_i32 s31, s31, 0x10000
	v_mfma_f32_16x16x32_bf16 v[106:109], v[174:177], v[182:185], v[106:109]
	v_mfma_f32_16x16x32_bf16 v[74:77], v[170:173], v[182:185], v[74:77]
	v_mfma_f32_16x16x32_bf16 v[42:45], v[166:169], v[182:185], v[42:45]
	v_mfma_f32_16x16x32_bf16 v[10:13], v[162:165], v[182:185], v[10:13]
	v_mfma_f32_16x16x32_bf16 v[98:101], v[174:177], v[178:181], v[98:101]
	v_mfma_f32_16x16x32_bf16 v[66:69], v[170:173], v[178:181], v[66:69]
	v_mfma_f32_16x16x32_bf16 v[34:37], v[166:169], v[178:181], v[34:37]
	v_mfma_f32_16x16x32_bf16 v[2:5], v[162:165], v[178:181], v[2:5]
	s_waitcnt vmcnt(0)
	s_waitcnt lgkmcnt(0)
	s_barrier
	v_mfma_f32_16x16x32_bf16 v[158:161], v[122:125], v[150:153], v[158:161]
	v_mfma_f32_16x16x32_bf16 v[94:97], v[126:129], v[150:153], v[94:97]
	s_add_i32 s28, s31, 0xfffe8000
	s_and_b32 s34, s28, 0x10000
	v_add_u32_e32 v170, s34, v230
	ds_read_b128 v[162:165], v170
	v_mfma_f32_16x16x32_bf16 v[62:65], v[130:133], v[150:153], v[62:65]
	ds_read_b128 v[166:169], v170 offset:1024
	v_mfma_f32_16x16x32_bf16 v[30:33], v[134:137], v[150:153], v[30:33]
	ds_read_b128 v[232:235], v170 offset:2048
	v_mfma_f32_16x16x32_bf16 v[118:121], v[122:125], v[146:149], v[118:121]
	ds_read_b128 v[236:239], v170 offset:3072
	v_mfma_f32_16x16x32_bf16 v[86:89], v[126:129], v[146:149], v[86:89]
	v_mfma_f32_16x16x32_bf16 v[54:57], v[130:133], v[146:149], v[54:57]
	v_mfma_f32_16x16x32_bf16 v[22:25], v[134:137], v[146:149], v[22:25]
	v_mfma_f32_16x16x32_bf16 v[110:113], v[122:125], v[142:145], v[110:113]
	v_mfma_f32_16x16x32_bf16 v[78:81], v[126:129], v[142:145], v[78:81]
	v_mfma_f32_16x16x32_bf16 v[46:49], v[130:133], v[142:145], v[46:49]
	v_mfma_f32_16x16x32_bf16 v[14:17], v[134:137], v[142:145], v[14:17]
	v_mfma_f32_16x16x32_bf16 v[102:105], v[122:125], v[138:141], v[102:105]
	v_mfma_f32_16x16x32_bf16 v[70:73], v[126:129], v[138:141], v[70:73]
	v_mfma_f32_16x16x32_bf16 v[38:41], v[130:133], v[138:141], v[38:41]
	v_mfma_f32_16x16x32_bf16 v[6:9], v[134:137], v[138:141], v[6:9]
	s_waitcnt lgkmcnt(0)
	v_mfma_f32_16x16x32_bf16 v[154:157], v[122:125], v[162:165], v[154:157]
	s_add_i32 s28, s31, 0xffff0000
	s_and_b32 s35, s28, 0x18000
	v_add_u32_e32 v187, s35, v200
	v_add_u32_e32 v226, s35, v201
	ds_read_b128 v[150:153], v226
	v_mfma_f32_16x16x32_bf16 v[90:93], v[126:129], v[162:165], v[90:93]
	ds_read_b128 v[146:149], v226 offset:1024
	v_mfma_f32_16x16x32_bf16 v[58:61], v[130:133], v[162:165], v[58:61]
	ds_read_b128 v[142:145], v226 offset:2048
	v_mfma_f32_16x16x32_bf16 v[26:29], v[134:137], v[162:165], v[26:29]
	ds_read_b128 v[138:141], v226 offset:3072
	v_mfma_f32_16x16x32_bf16 v[114:117], v[122:125], v[166:169], v[114:117]
	ds_read_b128 v[174:177], v187
	v_mfma_f32_16x16x32_bf16 v[82:85], v[126:129], v[166:169], v[82:85]
	ds_read_b128 v[170:173], v187 offset:1024
	v_mfma_f32_16x16x32_bf16 v[50:53], v[130:133], v[166:169], v[50:53]
	ds_read_b128 v[162:165], v187 offset:3072
	v_mfma_f32_16x16x32_bf16 v[18:21], v[134:137], v[166:169], v[18:21]
	ds_read_b128 v[166:169], v187 offset:2048
	v_mfma_f32_16x16x32_bf16 v[106:109], v[122:125], v[232:235], v[106:109]
	v_mfma_f32_16x16x32_bf16 v[74:77], v[126:129], v[232:235], v[74:77]
	v_mfma_f32_16x16x32_bf16 v[42:45], v[130:133], v[232:235], v[42:45]
	v_mfma_f32_16x16x32_bf16 v[10:13], v[134:137], v[232:235], v[10:13]
	v_mfma_f32_16x16x32_bf16 v[98:101], v[122:125], v[236:239], v[98:101]
	v_mfma_f32_16x16x32_bf16 v[66:69], v[126:129], v[236:239], v[66:69]
	v_mfma_f32_16x16x32_bf16 v[34:37], v[130:133], v[236:239], v[34:37]
	v_mfma_f32_16x16x32_bf16 v[2:5], v[134:137], v[236:239], v[2:5]
	s_waitcnt vmcnt(0)
	s_waitcnt lgkmcnt(0)
	s_barrier
	v_mfma_f32_16x16x32_bf16 v[158:161], v[174:177], v[150:153], v[158:161]
	v_mfma_f32_16x16x32_bf16 v[94:97], v[170:173], v[150:153], v[94:97]
	v_add_u32_e32 v226, s35, v230
	ds_read_b128 v[232:235], v226
	v_mfma_f32_16x16x32_bf16 v[62:65], v[166:169], v[150:153], v[62:65]
	ds_read_b128 v[236:239], v226 offset:1024
	v_mfma_f32_16x16x32_bf16 v[30:33], v[162:165], v[150:153], v[30:33]
	ds_read_b128 v[182:185], v226 offset:2048
	v_mfma_f32_16x16x32_bf16 v[118:121], v[174:177], v[146:149], v[118:121]
	ds_read_b128 v[178:181], v226 offset:3072
	v_mfma_f32_16x16x32_bf16 v[86:89], v[170:173], v[146:149], v[86:89]
	v_mfma_f32_16x16x32_bf16 v[54:57], v[166:169], v[146:149], v[54:57]
	v_mfma_f32_16x16x32_bf16 v[22:25], v[162:165], v[146:149], v[22:25]
	v_mfma_f32_16x16x32_bf16 v[110:113], v[174:177], v[142:145], v[110:113]
	v_mfma_f32_16x16x32_bf16 v[78:81], v[170:173], v[142:145], v[78:81]
	v_mfma_f32_16x16x32_bf16 v[46:49], v[166:169], v[142:145], v[46:49]
	v_mfma_f32_16x16x32_bf16 v[14:17], v[162:165], v[142:145], v[14:17]
	v_mfma_f32_16x16x32_bf16 v[102:105], v[174:177], v[138:141], v[102:105]
	v_mfma_f32_16x16x32_bf16 v[70:73], v[170:173], v[138:141], v[70:73]
	v_mfma_f32_16x16x32_bf16 v[38:41], v[166:169], v[138:141], v[38:41]
	v_mfma_f32_16x16x32_bf16 v[6:9], v[162:165], v[138:141], v[6:9]
	s_waitcnt lgkmcnt(0)
	v_mfma_f32_16x16x32_bf16 v[154:157], v[174:177], v[232:235], v[154:157]
	v_mfma_f32_16x16x32_bf16 v[90:93], v[170:173], v[232:235], v[90:93]
	v_mfma_f32_16x16x32_bf16 v[58:61], v[166:169], v[232:235], v[58:61]
	v_mfma_f32_16x16x32_bf16 v[26:29], v[162:165], v[232:235], v[26:29]
	v_mfma_f32_16x16x32_bf16 v[114:117], v[174:177], v[236:239], v[114:117]
	v_mfma_f32_16x16x32_bf16 v[82:85], v[170:173], v[236:239], v[82:85]
	v_mfma_f32_16x16x32_bf16 v[50:53], v[166:169], v[236:239], v[50:53]
	v_mfma_f32_16x16x32_bf16 v[18:21], v[162:165], v[236:239], v[18:21]
	s_add_i32 s19, s19, 2
	s_add_u32 s20, s20, 0x80
	s_addc_u32 s21, s21, 0
	s_add_i32 s31, s31, 0x10000
	v_mfma_f32_16x16x32_bf16 v[106:109], v[174:177], v[182:185], v[106:109]
	v_mfma_f32_16x16x32_bf16 v[74:77], v[170:173], v[182:185], v[74:77]
	v_mfma_f32_16x16x32_bf16 v[42:45], v[166:169], v[182:185], v[42:45]
	v_mfma_f32_16x16x32_bf16 v[10:13], v[162:165], v[182:185], v[10:13]
	v_mfma_f32_16x16x32_bf16 v[98:101], v[174:177], v[178:181], v[98:101]
	v_mfma_f32_16x16x32_bf16 v[66:69], v[170:173], v[178:181], v[66:69]
	v_mfma_f32_16x16x32_bf16 v[34:37], v[166:169], v[178:181], v[34:37]
	v_mfma_f32_16x16x32_bf16 v[2:5], v[162:165], v[178:181], v[2:5]
	s_branch .LBB0_197

.Lgr_G4x_tail:
	s_waitcnt lgkmcnt(0)
	v_mfma_f32_16x16x32_bf16 v[158:161], v[122:125], v[150:153], v[158:161]
	v_mfma_f32_16x16x32_bf16 v[94:97], v[126:129], v[150:153], v[94:97]
	s_add_i32 s28, s31, 0xfffe8000
	s_and_b32 s34, s28, 0x10000
	v_add_u32_e32 v170, s34, v230
	ds_read_b128 v[162:165], v170
	v_mfma_f32_16x16x32_bf16 v[62:65], v[130:133], v[150:153], v[62:65]
	ds_read_b128 v[166:169], v170 offset:1024
	v_mfma_f32_16x16x32_bf16 v[30:33], v[134:137], v[150:153], v[30:33]
	ds_read_b128 v[232:235], v170 offset:2048
	v_mfma_f32_16x16x32_bf16 v[118:121], v[122:125], v[146:149], v[118:121]
	ds_read_b128 v[236:239], v170 offset:3072
	s_and_b32 s89, s31, 0x18000
	s_add_i32 s89, s89, s88
	s_mov_b32 m0, s89
	v_mfma_f32_16x16x32_bf16 v[86:89], v[126:129], v[146:149], v[86:89]
	v_mfma_f32_16x16x32_bf16 v[54:57], v[130:133], v[146:149], v[54:57]
	global_load_lds_dwordx4 v186, s[90:91]
	s_add_i32 m0, s89, 0x2000
	v_mfma_f32_16x16x32_bf16 v[22:25], v[134:137], v[146:149], v[22:25]
	v_mfma_f32_16x16x32_bf16 v[110:113], v[122:125], v[142:145], v[110:113]
	v_mfma_f32_16x16x32_bf16 v[78:81], v[126:129], v[142:145], v[78:81]
	global_load_lds_dwordx4 v188, s[90:91]
	s_add_i32 m0, s89, 0x4000
	v_mfma_f32_16x16x32_bf16 v[46:49], v[130:133], v[142:145], v[46:49]
	v_mfma_f32_16x16x32_bf16 v[14:17], v[134:137], v[142:145], v[14:17]
	global_load_lds_dwordx4 v190, s[92:93]
	s_add_i32 m0, s89, 0x6000
	v_mfma_f32_16x16x32_bf16 v[102:105], v[122:125], v[138:141], v[102:105]
	v_mfma_f32_16x16x32_bf16 v[70:73], v[126:129], v[138:141], v[70:73]
	global_load_lds_dwordx4 v192, s[92:93]
	s_add_u32 s90, s90, 64
	s_addc_u32 s91, s91, 0
	s_add_u32 s92, s92, 64
	s_addc_u32 s93, s93, 0
	v_mfma_f32_16x16x32_bf16 v[38:41], v[130:133], v[138:141], v[38:41]
	v_mfma_f32_16x16x32_bf16 v[6:9], v[134:137], v[138:141], v[6:9]
	s_waitcnt vmcnt(4)
	s_waitcnt lgkmcnt(0)
	s_barrier
	v_mfma_f32_16x16x32_bf16 v[154:157], v[122:125], v[162:165], v[154:157]
	s_add_i32 s28, s31, 0xffff0000
	s_and_b32 s35, s28, 0x18000
	v_add_u32_e32 v187, s35, v200
	v_add_u32_e32 v226, s35, v201
	ds_read_b128 v[150:153], v226
	v_mfma_f32_16x16x32_bf16 v[90:93], v[126:129], v[162:165], v[90:93]
	ds_read_b128 v[146:149], v226 offset:1024
	v_mfma_f32_16x16x32_bf16 v[58:61], v[130:133], v[162:165], v[58:61]
	ds_read_b128 v[142:145], v226 offset:2048
	v_mfma_f32_16x16x32_bf16 v[26:29], v[134:137], v[162:165], v[26:29]
	ds_read_b128 v[138:141], v226 offset:3072
	v_mfma_f32_16x16x32_bf16 v[114:117], v[122:125], v[166:169], v[114:117]
	ds_read_b128 v[174:177], v187
	v_mfma_f32_16x16x32_bf16 v[82:85], v[126:129], v[166:169], v[82:85]
	ds_read_b128 v[170:173], v187 offset:1024
	v_mfma_f32_16x16x32_bf16 v[50:53], v[130:133], v[166:169], v[50:53]
	ds_read_b128 v[162:165], v187 offset:3072
	v_mfma_f32_16x16x32_bf16 v[18:21], v[134:137], v[166:169], v[18:21]
	ds_read_b128 v[166:169], v187 offset:2048
	v_mfma_f32_16x16x32_bf16 v[106:109], v[122:125], v[232:235], v[106:109]
	v_mfma_f32_16x16x32_bf16 v[74:77], v[126:129], v[232:235], v[74:77]
	v_mfma_f32_16x16x32_bf16 v[42:45], v[130:133], v[232:235], v[42:45]
	v_mfma_f32_16x16x32_bf16 v[10:13], v[134:137], v[232:235], v[10:13]
	v_mfma_f32_16x16x32_bf16 v[98:101], v[122:125], v[236:239], v[98:101]
	v_mfma_f32_16x16x32_bf16 v[66:69], v[126:129], v[236:239], v[66:69]
	v_mfma_f32_16x16x32_bf16 v[34:37], v[130:133], v[236:239], v[34:37]
	v_mfma_f32_16x16x32_bf16 v[2:5], v[134:137], v[236:239], v[2:5]
	s_waitcnt lgkmcnt(0)
	v_mfma_f32_16x16x32_bf16 v[158:161], v[174:177], v[150:153], v[158:161]
	v_mfma_f32_16x16x32_bf16 v[94:97], v[170:173], v[150:153], v[94:97]
	v_add_u32_e32 v226, s35, v230
	ds_read_b128 v[232:235], v226
	v_mfma_f32_16x16x32_bf16 v[62:65], v[166:169], v[150:153], v[62:65]
	ds_read_b128 v[236:239], v226 offset:1024
	v_mfma_f32_16x16x32_bf16 v[30:33], v[162:165], v[150:153], v[30:33]
	ds_read_b128 v[182:185], v226 offset:2048
	v_mfma_f32_16x16x32_bf16 v[118:121], v[174:177], v[146:149], v[118:121]
	ds_read_b128 v[178:181], v226 offset:3072
	v_mfma_f32_16x16x32_bf16 v[86:89], v[170:173], v[146:149], v[86:89]
	v_mfma_f32_16x16x32_bf16 v[54:57], v[166:169], v[146:149], v[54:57]
	v_mfma_f32_16x16x32_bf16 v[22:25], v[162:165], v[146:149], v[22:25]
	v_mfma_f32_16x16x32_bf16 v[110:113], v[174:177], v[142:145], v[110:113]
	v_mfma_f32_16x16x32_bf16 v[78:81], v[170:173], v[142:145], v[78:81]
	v_mfma_f32_16x16x32_bf16 v[46:49], v[166:169], v[142:145], v[46:49]
	v_mfma_f32_16x16x32_bf16 v[14:17], v[162:165], v[142:145], v[14:17]
	v_mfma_f32_16x16x32_bf16 v[102:105], v[174:177], v[138:141], v[102:105]
	v_mfma_f32_16x16x32_bf16 v[70:73], v[170:173], v[138:141], v[70:73]
	v_mfma_f32_16x16x32_bf16 v[38:41], v[166:169], v[138:141], v[38:41]
	v_mfma_f32_16x16x32_bf16 v[6:9], v[162:165], v[138:141], v[6:9]
	s_waitcnt vmcnt(0)
	s_waitcnt lgkmcnt(0)
	s_barrier
	v_mfma_f32_16x16x32_bf16 v[154:157], v[174:177], v[232:235], v[154:157]
	s_add_i32 s24, s31, 0xffff8000
	s_and_b32 s24, s24, 0x10000
	v_add_u32_e32 v187, s24, v200
	v_add_u32_e32 v226, s24, v201
	ds_read_b128 v[150:153], v226
	v_mfma_f32_16x16x32_bf16 v[90:93], v[170:173], v[232:235], v[90:93]
	ds_read_b128 v[146:149], v226 offset:1024
	v_mfma_f32_16x16x32_bf16 v[58:61], v[166:169], v[232:235], v[58:61]
	ds_read_b128 v[142:145], v226 offset:2048
	v_mfma_f32_16x16x32_bf16 v[26:29], v[162:165], v[232:235], v[26:29]
	ds_read_b128 v[138:141], v226 offset:3072
	v_mfma_f32_16x16x32_bf16 v[114:117], v[174:177], v[236:239], v[114:117]
	ds_read_b128 v[122:125], v187
	v_mfma_f32_16x16x32_bf16 v[82:85], v[170:173], v[236:239], v[82:85]
	ds_read_b128 v[126:129], v187 offset:1024
	v_mfma_f32_16x16x32_bf16 v[50:53], v[166:169], v[236:239], v[50:53]
	ds_read_b128 v[130:133], v187 offset:2048
	v_mfma_f32_16x16x32_bf16 v[18:21], v[162:165], v[236:239], v[18:21]
	ds_read_b128 v[134:137], v187 offset:3072
	s_add_i32 s19, s19, 2
	s_add_u32 s20, s20, 0x80
	s_addc_u32 s21, s21, 0
	s_add_i32 s31, s31, 0x10000
	v_mfma_f32_16x16x32_bf16 v[106:109], v[174:177], v[182:185], v[106:109]
	v_mfma_f32_16x16x32_bf16 v[74:77], v[170:173], v[182:185], v[74:77]
	v_mfma_f32_16x16x32_bf16 v[42:45], v[166:169], v[182:185], v[42:45]
	v_mfma_f32_16x16x32_bf16 v[10:13], v[162:165], v[182:185], v[10:13]
	v_mfma_f32_16x16x32_bf16 v[98:101], v[174:177], v[178:181], v[98:101]
	v_mfma_f32_16x16x32_bf16 v[66:69], v[170:173], v[178:181], v[66:69]
	v_mfma_f32_16x16x32_bf16 v[34:37], v[166:169], v[178:181], v[34:37]
	v_mfma_f32_16x16x32_bf16 v[2:5], v[162:165], v[178:181], v[2:5]
	s_waitcnt lgkmcnt(0)
	v_mfma_f32_16x16x32_bf16 v[158:161], v[122:125], v[150:153], v[158:161]
	v_mfma_f32_16x16x32_bf16 v[94:97], v[126:129], v[150:153], v[94:97]
	s_add_i32 s28, s31, 0xfffe8000
	s_and_b32 s34, s28, 0x10000
	v_add_u32_e32 v170, s34, v230
	ds_read_b128 v[162:165], v170
	v_mfma_f32_16x16x32_bf16 v[62:65], v[130:133], v[150:153], v[62:65]
	ds_read_b128 v[166:169], v170 offset:1024
	v_mfma_f32_16x16x32_bf16 v[30:33], v[134:137], v[150:153], v[30:33]
	ds_read_b128 v[232:235], v170 offset:2048
	v_mfma_f32_16x16x32_bf16 v[118:121], v[122:125], v[146:149], v[118:121]
	ds_read_b128 v[236:239], v170 offset:3072
	v_mfma_f32_16x16x32_bf16 v[86:89], v[126:129], v[146:149], v[86:89]
	v_mfma_f32_16x16x32_bf16 v[54:57], v[130:133], v[146:149], v[54:57]
	v_mfma_f32_16x16x32_bf16 v[22:25], v[134:137], v[146:149], v[22:25]
	v_mfma_f32_16x16x32_bf16 v[110:113], v[122:125], v[142:145], v[110:113]
	v_mfma_f32_16x16x32_bf16 v[78:81], v[126:129], v[142:145], v[78:81]
	v_mfma_f32_16x16x32_bf16 v[46:49], v[130:133], v[142:145], v[46:49]
	v_mfma_f32_16x16x32_bf16 v[14:17], v[134:137], v[142:145], v[14:17]
	v_mfma_f32_16x16x32_bf16 v[102:105], v[122:125], v[138:141], v[102:105]
	v_mfma_f32_16x16x32_bf16 v[70:73], v[126:129], v[138:141], v[70:73]
	v_mfma_f32_16x16x32_bf16 v[38:41], v[130:133], v[138:141], v[38:41]
	v_mfma_f32_16x16x32_bf16 v[6:9], v[134:137], v[138:141], v[6:9]
	s_waitcnt vmcnt(0)
	s_waitcnt lgkmcnt(0)
	s_barrier
	v_mfma_f32_16x16x32_bf16 v[154:157], v[122:125], v[162:165], v[154:157]
	s_add_i32 s28, s31, 0xffff0000
	s_and_b32 s35, s28, 0x18000
	v_add_u32_e32 v187, s35, v200
	v_add_u32_e32 v226, s35, v201
	ds_read_b128 v[150:153], v226
	v_mfma_f32_16x16x32_bf16 v[90:93], v[126:129], v[162:165], v[90:93]
	ds_read_b128 v[146:149], v226 offset:1024
	v_mfma_f32_16x16x32_bf16 v[58:61], v[130:133], v[162:165], v[58:61]
	ds_read_b128 v[142:145], v226 offset:2048
	v_mfma_f32_16x16x32_bf16 v[26:29], v[134:137], v[162:165], v[26:29]
	ds_read_b128 v[138:141], v226 offset:3072
	v_mfma_f32_16x16x32_bf16 v[114:117], v[122:125], v[166:169], v[114:117]
	ds_read_b128 v[174:177], v187
	v_mfma_f32_16x16x32_bf16 v[82:85], v[126:129], v[166:169], v[82:85]
	ds_read_b128 v[170:173], v187 offset:1024
	v_mfma_f32_16x16x32_bf16 v[50:53], v[130:133], v[166:169], v[50:53]
	ds_read_b128 v[162:165], v187 offset:3072
	v_mfma_f32_16x16x32_bf16 v[18:21], v[134:137], v[166:169], v[18:21]
	ds_read_b128 v[166:169], v187 offset:2048
	v_mfma_f32_16x16x32_bf16 v[106:109], v[122:125], v[232:235], v[106:109]
	v_mfma_f32_16x16x32_bf16 v[74:77], v[126:129], v[232:235], v[74:77]
	v_mfma_f32_16x16x32_bf16 v[42:45], v[130:133], v[232:235], v[42:45]
	v_mfma_f32_16x16x32_bf16 v[10:13], v[134:137], v[232:235], v[10:13]
	v_mfma_f32_16x16x32_bf16 v[98:101], v[122:125], v[236:239], v[98:101]
	v_mfma_f32_16x16x32_bf16 v[66:69], v[126:129], v[236:239], v[66:69]
	v_mfma_f32_16x16x32_bf16 v[34:37], v[130:133], v[236:239], v[34:37]
	v_mfma_f32_16x16x32_bf16 v[2:5], v[134:137], v[236:239], v[2:5]
	s_waitcnt lgkmcnt(0)
	v_mfma_f32_16x16x32_bf16 v[158:161], v[174:177], v[150:153], v[158:161]
	v_mfma_f32_16x16x32_bf16 v[94:97], v[170:173], v[150:153], v[94:97]
	v_add_u32_e32 v226, s35, v230
	ds_read_b128 v[232:235], v226
	v_mfma_f32_16x16x32_bf16 v[62:65], v[166:169], v[150:153], v[62:65]
	ds_read_b128 v[236:239], v226 offset:1024
	v_mfma_f32_16x16x32_bf16 v[30:33], v[162:165], v[150:153], v[30:33]
	ds_read_b128 v[182:185], v226 offset:2048
	v_mfma_f32_16x16x32_bf16 v[118:121], v[174:177], v[146:149], v[118:121]
	ds_read_b128 v[178:181], v226 offset:3072
	v_mfma_f32_16x16x32_bf16 v[86:89], v[170:173], v[146:149], v[86:89]
	v_mfma_f32_16x16x32_bf16 v[54:57], v[166:169], v[146:149], v[54:57]
	v_mfma_f32_16x16x32_bf16 v[22:25], v[162:165], v[146:149], v[22:25]
	v_mfma_f32_16x16x32_bf16 v[110:113], v[174:177], v[142:145], v[110:113]
	v_mfma_f32_16x16x32_bf16 v[78:81], v[170:173], v[142:145], v[78:81]
	v_mfma_f32_16x16x32_bf16 v[46:49], v[166:169], v[142:145], v[46:49]
	v_mfma_f32_16x16x32_bf16 v[14:17], v[162:165], v[142:145], v[14:17]
	v_mfma_f32_16x16x32_bf16 v[102:105], v[174:177], v[138:141], v[102:105]
	v_mfma_f32_16x16x32_bf16 v[70:73], v[170:173], v[138:141], v[70:73]
	v_mfma_f32_16x16x32_bf16 v[38:41], v[166:169], v[138:141], v[38:41]
	v_mfma_f32_16x16x32_bf16 v[6:9], v[162:165], v[138:141], v[6:9]
	s_waitcnt vmcnt(0)
	s_waitcnt lgkmcnt(0)
	s_barrier
	v_mfma_f32_16x16x32_bf16 v[154:157], v[174:177], v[232:235], v[154:157]
	v_mfma_f32_16x16x32_bf16 v[90:93], v[170:173], v[232:235], v[90:93]
	v_mfma_f32_16x16x32_bf16 v[58:61], v[166:169], v[232:235], v[58:61]
	v_mfma_f32_16x16x32_bf16 v[26:29], v[162:165], v[232:235], v[26:29]
	v_mfma_f32_16x16x32_bf16 v[114:117], v[174:177], v[236:239], v[114:117]
	v_mfma_f32_16x16x32_bf16 v[82:85], v[170:173], v[236:239], v[82:85]
	v_mfma_f32_16x16x32_bf16 v[50:53], v[166:169], v[236:239], v[50:53]
	v_mfma_f32_16x16x32_bf16 v[18:21], v[162:165], v[236:239], v[18:21]
	s_add_i32 s19, s19, 2
	s_add_u32 s20, s20, 0x80
	s_addc_u32 s21, s21, 0
	s_add_i32 s31, s31, 0x10000
	v_mfma_f32_16x16x32_bf16 v[106:109], v[174:177], v[182:185], v[106:109]
	v_mfma_f32_16x16x32_bf16 v[74:77], v[170:173], v[182:185], v[74:77]
	v_mfma_f32_16x16x32_bf16 v[42:45], v[166:169], v[182:185], v[42:45]
	v_mfma_f32_16x16x32_bf16 v[10:13], v[162:165], v[182:185], v[10:13]
	v_mfma_f32_16x16x32_bf16 v[98:101], v[174:177], v[178:181], v[98:101]
	v_mfma_f32_16x16x32_bf16 v[66:69], v[170:173], v[178:181], v[66:69]
	v_mfma_f32_16x16x32_bf16 v[34:37], v[166:169], v[178:181], v[34:37]
	v_mfma_f32_16x16x32_bf16 v[2:5], v[162:165], v[178:181], v[2:5]
	s_branch .LBB0_197

.Lgf_G3x_top:
	s_waitcnt vmcnt(3)
	s_waitcnt lgkmcnt(0)
	s_barrier
	v_mfma_f32_16x16x32_bf16 v[102:105], v[2:5], v[26:29], v[102:105]
	v_mfma_f32_16x16x32_bf16 v[98:101], v[6:9], v[26:29], v[98:101]
	s_add_i32 s17, s8, -3
	s_and_b32 s19, s17, 2
	s_mulk_i32 s19, 0x6000
	v_add_u32_e32 v110, s19, v142
	ds_read_b128 v[106:109], v110
	v_mfma_f32_16x16x32_bf16 v[86:89], v[10:13], v[26:29], v[86:89]
	ds_read_b128 v[144:147], v110 offset:1024
	s_and_b32 s69, s8, 3
	s_mulk_i32 s69, 0x6000
	s_add_i32 s69, s69, s29
	s_mov_b32 m0, s69
	v_mfma_f32_16x16x32_bf16 v[70:73], v[14:17], v[26:29], v[70:73]
	v_mfma_f32_16x16x32_bf16 v[90:93], v[2:5], v[22:25], v[90:93]
	global_load_lds_dwordx4 v126, s[44:45]
	s_add_i32 m0, s69, 0x2000
	v_mfma_f32_16x16x32_bf16 v[78:81], v[6:9], v[22:25], v[78:81]
	global_load_lds_dwordx4 v128, s[44:45]
	s_add_i32 m0, s69, 0x4000
	v_mfma_f32_16x16x32_bf16 v[62:65], v[10:13], v[22:25], v[62:65]
	global_load_lds_dwordx4 v130, s[30:31]
	s_add_u32 s44, s44, 64
	s_addc_u32 s45, s45, 0
	s_add_u32 s30, s30, 64
	s_addc_u32 s31, s31, 0
	v_mfma_f32_16x16x32_bf16 v[46:49], v[14:17], v[22:25], v[46:49]
	s_waitcnt lgkmcnt(0)
	v_mfma_f32_16x16x32_bf16 v[74:77], v[2:5], v[106:109], v[74:77]
	s_add_i32 s26, s8, -2
	s_and_b32 s28, s26, 3
	s_mulk_i32 s28, 0x6000
	v_add_u32_e32 v127, s28, v140
	v_add_u32_e32 v143, s28, v141
	ds_read_b128 v[26:29], v143
	v_mfma_f32_16x16x32_bf16 v[58:61], v[6:9], v[106:109], v[58:61]
	ds_read_b128 v[22:25], v143 offset:1024
	v_mfma_f32_16x16x32_bf16 v[38:41], v[10:13], v[106:109], v[38:41]
	ds_read_b128 v[118:121], v127
	v_mfma_f32_16x16x32_bf16 v[30:33], v[14:17], v[106:109], v[30:33]
	ds_read_b128 v[114:117], v127 offset:1024
	ds_read_b128 v[110:113], v127 offset:2048
	ds_read_b128 v[106:109], v127 offset:3072
	v_mfma_f32_16x16x32_bf16 v[94:97], v[2:5], v[144:147], v[94:97]
	v_mfma_f32_16x16x32_bf16 v[82:85], v[6:9], v[144:147], v[82:85]
	v_mfma_f32_16x16x32_bf16 v[66:69], v[10:13], v[144:147], v[66:69]
	v_mfma_f32_16x16x32_bf16 v[34:37], v[14:17], v[144:147], v[34:37]
	s_waitcnt vmcnt(3)
	s_waitcnt lgkmcnt(0)
	s_barrier
	v_mfma_f32_16x16x32_bf16 v[102:105], v[118:121], v[26:29], v[102:105]
	v_mfma_f32_16x16x32_bf16 v[98:101], v[114:117], v[26:29], v[98:101]
	v_add_u32_e32 v132, s28, v142
	ds_read_b128 v[144:147], v132
	v_mfma_f32_16x16x32_bf16 v[86:89], v[110:113], v[26:29], v[86:89]
	ds_read_b128 v[122:125], v132 offset:1024
	s_add_i32 s69, s19, s29
	s_mov_b32 m0, s69
	v_mfma_f32_16x16x32_bf16 v[70:73], v[106:109], v[26:29], v[70:73]
	v_mfma_f32_16x16x32_bf16 v[90:93], v[118:121], v[22:25], v[90:93]
	global_load_lds_dwordx4 v126, s[44:45]
	s_add_i32 m0, s69, 0x2000
	v_mfma_f32_16x16x32_bf16 v[78:81], v[114:117], v[22:25], v[78:81]
	global_load_lds_dwordx4 v128, s[44:45]
	s_add_i32 m0, s69, 0x4000
	v_mfma_f32_16x16x32_bf16 v[62:65], v[110:113], v[22:25], v[62:65]
	global_load_lds_dwordx4 v130, s[30:31]
	s_add_u32 s44, s44, 64
	s_addc_u32 s45, s45, 0
	s_add_u32 s30, s30, 64
	s_addc_u32 s31, s31, 0
	v_mfma_f32_16x16x32_bf16 v[46:49], v[106:109], v[22:25], v[46:49]
	s_waitcnt lgkmcnt(0)
	v_mfma_f32_16x16x32_bf16 v[74:77], v[118:121], v[144:147], v[74:77]
	s_add_i32 s19, s8, -1
	s_and_b32 s19, s19, 2
	s_mulk_i32 s19, 0x6000
	v_add_u32_e32 v127, s19, v140
	v_add_u32_e32 v132, s19, v141
	ds_read_b128 v[26:29], v132
	v_mfma_f32_16x16x32_bf16 v[58:61], v[114:117], v[144:147], v[58:61]
	ds_read_b128 v[22:25], v132 offset:1024
	v_mfma_f32_16x16x32_bf16 v[38:41], v[110:113], v[144:147], v[38:41]
	ds_read_b128 v[2:5], v127
	v_mfma_f32_16x16x32_bf16 v[30:33], v[106:109], v[144:147], v[30:33]
	ds_read_b128 v[6:9], v127 offset:1024
	ds_read_b128 v[10:13], v127 offset:2048
	ds_read_b128 v[14:17], v127 offset:3072
	s_add_u32 s20, s20, 0x80
	s_addc_u32 s21, s21, 0
	s_add_i32 s8, s8, 2
	s_cmp_gt_u32 s17, 29
	v_mfma_f32_16x16x32_bf16 v[94:97], v[118:121], v[122:125], v[94:97]
	v_mfma_f32_16x16x32_bf16 v[82:85], v[114:117], v[122:125], v[82:85]
	v_mfma_f32_16x16x32_bf16 v[66:69], v[110:113], v[122:125], v[66:69]
	v_mfma_f32_16x16x32_bf16 v[34:37], v[106:109], v[122:125], v[34:37]
	s_cmp_lt_u32 s8, 30
	s_cbranch_scc1 .Lgf_G3x_top
	s_waitcnt vmcnt(3)
	s_waitcnt lgkmcnt(0)
	s_barrier
	v_mfma_f32_16x16x32_bf16 v[102:105], v[2:5], v[26:29], v[102:105]
	v_mfma_f32_16x16x32_bf16 v[98:101], v[6:9], v[26:29], v[98:101]
	s_add_i32 s17, s8, -3
	s_and_b32 s19, s17, 2
	s_mulk_i32 s19, 0x6000
	v_add_u32_e32 v110, s19, v142
	ds_read_b128 v[106:109], v110
	v_mfma_f32_16x16x32_bf16 v[86:89], v[10:13], v[26:29], v[86:89]
	ds_read_b128 v[144:147], v110 offset:1024
	s_and_b32 s69, s8, 3
	s_mulk_i32 s69, 0x6000
	s_add_i32 s69, s69, s29
	s_mov_b32 m0, s69
	v_mfma_f32_16x16x32_bf16 v[70:73], v[14:17], v[26:29], v[70:73]
	v_mfma_f32_16x16x32_bf16 v[90:93], v[2:5], v[22:25], v[90:93]
	global_load_lds_dwordx4 v126, s[44:45]
	s_add_i32 m0, s69, 0x2000
	v_mfma_f32_16x16x32_bf16 v[78:81], v[6:9], v[22:25], v[78:81]
	global_load_lds_dwordx4 v128, s[44:45]
	s_add_i32 m0, s69, 0x4000
	v_mfma_f32_16x16x32_bf16 v[62:65], v[10:13], v[22:25], v[62:65]
	global_load_lds_dwordx4 v130, s[30:31]
	s_add_u32 s44, s44, 64
	s_addc_u32 s45, s45, 0
	s_add_u32 s30, s30, 64
	s_addc_u32 s31, s31, 0
	v_mfma_f32_16x16x32_bf16 v[46:49], v[14:17], v[22:25], v[46:49]
	s_waitcnt lgkmcnt(0)
	v_mfma_f32_16x16x32_bf16 v[74:77], v[2:5], v[106:109], v[74:77]
	s_add_i32 s26, s8, -2
	s_and_b32 s28, s26, 3
	s_mulk_i32 s28, 0x6000
	v_add_u32_e32 v127, s28, v140
	v_add_u32_e32 v143, s28, v141
	ds_read_b128 v[26:29], v143
	v_mfma_f32_16x16x32_bf16 v[58:61], v[6:9], v[106:109], v[58:61]
	ds_read_b128 v[22:25], v143 offset:1024
	v_mfma_f32_16x16x32_bf16 v[38:41], v[10:13], v[106:109], v[38:41]
	ds_read_b128 v[118:121], v127
	v_mfma_f32_16x16x32_bf16 v[30:33], v[14:17], v[106:109], v[30:33]
	ds_read_b128 v[114:117], v127 offset:1024
	ds_read_b128 v[110:113], v127 offset:2048
	ds_read_b128 v[106:109], v127 offset:3072
	v_mfma_f32_16x16x32_bf16 v[94:97], v[2:5], v[144:147], v[94:97]
	v_mfma_f32_16x16x32_bf16 v[82:85], v[6:9], v[144:147], v[82:85]
	v_mfma_f32_16x16x32_bf16 v[66:69], v[10:13], v[144:147], v[66:69]
	v_mfma_f32_16x16x32_bf16 v[34:37], v[14:17], v[144:147], v[34:37]
	s_waitcnt vmcnt(3)
	s_waitcnt lgkmcnt(0)
	s_barrier
	v_mfma_f32_16x16x32_bf16 v[102:105], v[118:121], v[26:29], v[102:105]
	v_mfma_f32_16x16x32_bf16 v[98:101], v[114:117], v[26:29], v[98:101]
	v_add_u32_e32 v132, s28, v142
	ds_read_b128 v[144:147], v132
	v_mfma_f32_16x16x32_bf16 v[86:89], v[110:113], v[26:29], v[86:89]
	ds_read_b128 v[122:125], v132 offset:1024
	v_mfma_f32_16x16x32_bf16 v[70:73], v[106:109], v[26:29], v[70:73]
	v_mfma_f32_16x16x32_bf16 v[90:93], v[118:121], v[22:25], v[90:93]
	v_mfma_f32_16x16x32_bf16 v[78:81], v[114:117], v[22:25], v[78:81]
	v_mfma_f32_16x16x32_bf16 v[62:65], v[110:113], v[22:25], v[62:65]
	v_mfma_f32_16x16x32_bf16 v[46:49], v[106:109], v[22:25], v[46:49]
	s_waitcnt lgkmcnt(0)
	v_mfma_f32_16x16x32_bf16 v[74:77], v[118:121], v[144:147], v[74:77]
	s_add_i32 s19, s8, -1
	s_and_b32 s19, s19, 2
	s_mulk_i32 s19, 0x6000
	v_add_u32_e32 v127, s19, v140
	v_add_u32_e32 v132, s19, v141
	ds_read_b128 v[26:29], v132
	v_mfma_f32_16x16x32_bf16 v[58:61], v[114:117], v[144:147], v[58:61]
	ds_read_b128 v[22:25], v132 offset:1024
	v_mfma_f32_16x16x32_bf16 v[38:41], v[110:113], v[144:147], v[38:41]
	ds_read_b128 v[2:5], v127
	v_mfma_f32_16x16x32_bf16 v[30:33], v[106:109], v[144:147], v[30:33]
	ds_read_b128 v[6:9], v127 offset:1024
	ds_read_b128 v[10:13], v127 offset:2048
	ds_read_b128 v[14:17], v127 offset:3072
	s_add_u32 s20, s20, 0x80
	s_addc_u32 s21, s21, 0
	s_add_i32 s8, s8, 2
	s_cmp_gt_u32 s17, 29
	v_mfma_f32_16x16x32_bf16 v[94:97], v[118:121], v[122:125], v[94:97]
	v_mfma_f32_16x16x32_bf16 v[82:85], v[114:117], v[122:125], v[82:85]
	v_mfma_f32_16x16x32_bf16 v[66:69], v[110:113], v[122:125], v[66:69]
	v_mfma_f32_16x16x32_bf16 v[34:37], v[106:109], v[122:125], v[34:37]
	s_waitcnt vmcnt(0)
	s_waitcnt lgkmcnt(0)
	s_barrier
	v_mfma_f32_16x16x32_bf16 v[102:105], v[2:5], v[26:29], v[102:105]
	v_mfma_f32_16x16x32_bf16 v[98:101], v[6:9], v[26:29], v[98:101]
	s_add_i32 s17, s8, -3
	s_and_b32 s19, s17, 2
	s_mulk_i32 s19, 0x6000
	v_add_u32_e32 v110, s19, v142
	ds_read_b128 v[106:109], v110
	v_mfma_f32_16x16x32_bf16 v[86:89], v[10:13], v[26:29], v[86:89]
	ds_read_b128 v[144:147], v110 offset:1024
	v_mfma_f32_16x16x32_bf16 v[70:73], v[14:17], v[26:29], v[70:73]
	v_mfma_f32_16x16x32_bf16 v[90:93], v[2:5], v[22:25], v[90:93]
	v_mfma_f32_16x16x32_bf16 v[78:81], v[6:9], v[22:25], v[78:81]
	v_mfma_f32_16x16x32_bf16 v[62:65], v[10:13], v[22:25], v[62:65]
	v_mfma_f32_16x16x32_bf16 v[46:49], v[14:17], v[22:25], v[46:49]
	s_waitcnt lgkmcnt(0)
	v_mfma_f32_16x16x32_bf16 v[74:77], v[2:5], v[106:109], v[74:77]
	s_add_i32 s26, s8, -2
	s_and_b32 s28, s26, 3
	s_mulk_i32 s28, 0x6000
	v_add_u32_e32 v127, s28, v140
	v_add_u32_e32 v143, s28, v141
	ds_read_b128 v[26:29], v143
	v_mfma_f32_16x16x32_bf16 v[58:61], v[6:9], v[106:109], v[58:61]
	ds_read_b128 v[22:25], v143 offset:1024
	v_mfma_f32_16x16x32_bf16 v[38:41], v[10:13], v[106:109], v[38:41]
	ds_read_b128 v[118:121], v127
	v_mfma_f32_16x16x32_bf16 v[30:33], v[14:17], v[106:109], v[30:33]
	ds_read_b128 v[114:117], v127 offset:1024
	ds_read_b128 v[110:113], v127 offset:2048
	ds_read_b128 v[106:109], v127 offset:3072
	v_mfma_f32_16x16x32_bf16 v[94:97], v[2:5], v[144:147], v[94:97]
	v_mfma_f32_16x16x32_bf16 v[82:85], v[6:9], v[144:147], v[82:85]
	v_mfma_f32_16x16x32_bf16 v[66:69], v[10:13], v[144:147], v[66:69]
	v_mfma_f32_16x16x32_bf16 v[34:37], v[14:17], v[144:147], v[34:37]
	s_waitcnt vmcnt(0)
	s_waitcnt lgkmcnt(0)
	s_barrier
	v_mfma_f32_16x16x32_bf16 v[102:105], v[118:121], v[26:29], v[102:105]
	v_mfma_f32_16x16x32_bf16 v[98:101], v[114:117], v[26:29], v[98:101]
	v_add_u32_e32 v132, s28, v142
	ds_read_b128 v[144:147], v132
	v_mfma_f32_16x16x32_bf16 v[86:89], v[110:113], v[26:29], v[86:89]
	ds_read_b128 v[122:125], v132 offset:1024
	v_mfma_f32_16x16x32_bf16 v[70:73], v[106:109], v[26:29], v[70:73]
	v_mfma_f32_16x16x32_bf16 v[90:93], v[118:121], v[22:25], v[90:93]
	v_mfma_f32_16x16x32_bf16 v[78:81], v[114:117], v[22:25], v[78:81]
	v_mfma_f32_16x16x32_bf16 v[62:65], v[110:113], v[22:25], v[62:65]
	v_mfma_f32_16x16x32_bf16 v[46:49], v[106:109], v[22:25], v[46:49]
	s_waitcnt lgkmcnt(0)
	v_mfma_f32_16x16x32_bf16 v[74:77], v[118:121], v[144:147], v[74:77]
	v_mfma_f32_16x16x32_bf16 v[58:61], v[114:117], v[144:147], v[58:61]
	v_mfma_f32_16x16x32_bf16 v[38:41], v[110:113], v[144:147], v[38:41]
	v_mfma_f32_16x16x32_bf16 v[30:33], v[106:109], v[144:147], v[30:33]
	s_add_u32 s20, s20, 0x80
	s_addc_u32 s21, s21, 0
	s_add_i32 s8, s8, 2
	s_cmp_gt_u32 s17, 29
	v_mfma_f32_16x16x32_bf16 v[94:97], v[118:121], v[122:125], v[94:97]
	v_mfma_f32_16x16x32_bf16 v[82:85], v[114:117], v[122:125], v[82:85]
	v_mfma_f32_16x16x32_bf16 v[66:69], v[110:113], v[122:125], v[66:69]
	v_mfma_f32_16x16x32_bf16 v[34:37], v[106:109], v[122:125], v[34:37]
	s_branch .LBB0_305

.Lgr_G3x_tail:
	s_waitcnt lgkmcnt(0)
	v_mfma_f32_16x16x32_bf16 v[102:105], v[2:5], v[26:29], v[102:105]
	v_mfma_f32_16x16x32_bf16 v[98:101], v[6:9], v[26:29], v[98:101]
	s_add_i32 s17, s8, -3
	s_and_b32 s19, s17, 2
	s_mulk_i32 s19, 0x6000
	v_add_u32_e32 v110, s19, v142
	ds_read_b128 v[106:109], v110
	v_mfma_f32_16x16x32_bf16 v[86:89], v[10:13], v[26:29], v[86:89]
	ds_read_b128 v[144:147], v110 offset:1024
	s_and_b32 s69, s8, 3
	s_mulk_i32 s69, 0x6000
	s_add_i32 s69, s69, s29
	s_mov_b32 m0, s69
	v_mfma_f32_16x16x32_bf16 v[70:73], v[14:17], v[26:29], v[70:73]
	v_mfma_f32_16x16x32_bf16 v[90:93], v[2:5], v[22:25], v[90:93]
	global_load_lds_dwordx4 v126, s[44:45]
	s_add_i32 m0, s69, 0x2000
	v_mfma_f32_16x16x32_bf16 v[78:81], v[6:9], v[22:25], v[78:81]
	global_load_lds_dwordx4 v128, s[44:45]
	s_add_i32 m0, s69, 0x4000
	v_mfma_f32_16x16x32_bf16 v[62:65], v[10:13], v[22:25], v[62:65]
	global_load_lds_dwordx4 v130, s[30:31]
	s_add_u32 s44, s44, 64
	s_addc_u32 s45, s45, 0
	s_add_u32 s30, s30, 64
	s_addc_u32 s31, s31, 0
	v_mfma_f32_16x16x32_bf16 v[46:49], v[14:17], v[22:25], v[46:49]
	s_waitcnt vmcnt(3)
	s_waitcnt lgkmcnt(0)
	s_barrier
	v_mfma_f32_16x16x32_bf16 v[74:77], v[2:5], v[106:109], v[74:77]
	s_add_i32 s26, s8, -2
	s_and_b32 s28, s26, 3
	s_mulk_i32 s28, 0x6000
	v_add_u32_e32 v127, s28, v140
	v_add_u32_e32 v143, s28, v141
	ds_read_b128 v[26:29], v143
	v_mfma_f32_16x16x32_bf16 v[58:61], v[6:9], v[106:109], v[58:61]
	ds_read_b128 v[22:25], v143 offset:1024
	v_mfma_f32_16x16x32_bf16 v[38:41], v[10:13], v[106:109], v[38:41]
	ds_read_b128 v[118:121], v127
	v_mfma_f32_16x16x32_bf16 v[30:33], v[14:17], v[106:109], v[30:33]
	ds_read_b128 v[114:117], v127 offset:1024
	ds_read_b128 v[110:113], v127 offset:2048
	ds_read_b128 v[106:109], v127 offset:3072
	v_mfma_f32_16x16x32_bf16 v[94:97], v[2:5], v[144:147], v[94:97]
	v_mfma_f32_16x16x32_bf16 v[82:85], v[6:9], v[144:147], v[82:85]
	v_mfma_f32_16x16x32_bf16 v[66:69], v[10:13], v[144:147], v[66:69]
	v_mfma_f32_16x16x32_bf16 v[34:37], v[14:17], v[144:147], v[34:37]
	s_waitcnt lgkmcnt(0)
	v_mfma_f32_16x16x32_bf16 v[102:105], v[118:121], v[26:29], v[102:105]
	v_mfma_f32_16x16x32_bf16 v[98:101], v[114:117], v[26:29], v[98:101]
	v_add_u32_e32 v132, s28, v142
	ds_read_b128 v[144:147], v132
	v_mfma_f32_16x16x32_bf16 v[86:89], v[110:113], v[26:29], v[86:89]
	ds_read_b128 v[122:125], v132 offset:1024
	v_mfma_f32_16x16x32_bf16 v[70:73], v[106:109], v[26:29], v[70:73]
	v_mfma_f32_16x16x32_bf16 v[90:93], v[118:121], v[22:25], v[90:93]
	v_mfma_f32_16x16x32_bf16 v[78:81], v[114:117], v[22:25], v[78:81]
	v_mfma_f32_16x16x32_bf16 v[62:65], v[110:113], v[22:25], v[62:65]
	v_mfma_f32_16x16x32_bf16 v[46:49], v[106:109], v[22:25], v[46:49]
	s_waitcnt vmcnt(0)
	s_waitcnt lgkmcnt(0)
	s_barrier
	v_mfma_f32_16x16x32_bf16 v[74:77], v[118:121], v[144:147], v[74:77]
	s_add_i32 s19, s8, -1
	s_and_b32 s19, s19, 2
	s_mulk_i32 s19, 0x6000
	v_add_u32_e32 v127, s19, v140
	v_add_u32_e32 v132, s19, v141
	ds_read_b128 v[26:29], v132
	v_mfma_f32_16x16x32_bf16 v[58:61], v[114:117], v[144:147], v[58:61]
	ds_read_b128 v[22:25], v132 offset:1024
	v_mfma_f32_16x16x32_bf16 v[38:41], v[110:113], v[144:147], v[38:41]
	ds_read_b128 v[2:5], v127
	v_mfma_f32_16x16x32_bf16 v[30:33], v[106:109], v[144:147], v[30:33]
	ds_read_b128 v[6:9], v127 offset:1024
	ds_read_b128 v[10:13], v127 offset:2048
	ds_read_b128 v[14:17], v127 offset:3072
	s_add_u32 s20, s20, 0x80
	s_addc_u32 s21, s21, 0
	s_add_i32 s8, s8, 2
	s_cmp_gt_u32 s17, 29
	v_mfma_f32_16x16x32_bf16 v[94:97], v[118:121], v[122:125], v[94:97]
	v_mfma_f32_16x16x32_bf16 v[82:85], v[114:117], v[122:125], v[82:85]
	v_mfma_f32_16x16x32_bf16 v[66:69], v[110:113], v[122:125], v[66:69]
	v_mfma_f32_16x16x32_bf16 v[34:37], v[106:109], v[122:125], v[34:37]
	s_waitcnt lgkmcnt(0)
	v_mfma_f32_16x16x32_bf16 v[102:105], v[2:5], v[26:29], v[102:105]
	v_mfma_f32_16x16x32_bf16 v[98:101], v[6:9], v[26:29], v[98:101]
	s_add_i32 s17, s8, -3
	s_and_b32 s19, s17, 2
	s_mulk_i32 s19, 0x6000
	v_add_u32_e32 v110, s19, v142
	ds_read_b128 v[106:109], v110
	v_mfma_f32_16x16x32_bf16 v[86:89], v[10:13], v[26:29], v[86:89]
	ds_read_b128 v[144:147], v110 offset:1024
	v_mfma_f32_16x16x32_bf16 v[70:73], v[14:17], v[26:29], v[70:73]
	v_mfma_f32_16x16x32_bf16 v[90:93], v[2:5], v[22:25], v[90:93]
	v_mfma_f32_16x16x32_bf16 v[78:81], v[6:9], v[22:25], v[78:81]
	v_mfma_f32_16x16x32_bf16 v[62:65], v[10:13], v[22:25], v[62:65]
	v_mfma_f32_16x16x32_bf16 v[46:49], v[14:17], v[22:25], v[46:49]
	s_waitcnt vmcnt(0)
	s_waitcnt lgkmcnt(0)
	s_barrier
	v_mfma_f32_16x16x32_bf16 v[74:77], v[2:5], v[106:109], v[74:77]
	s_add_i32 s26, s8, -2
	s_and_b32 s28, s26, 3
	s_mulk_i32 s28, 0x6000
	v_add_u32_e32 v127, s28, v140
	v_add_u32_e32 v143, s28, v141
	ds_read_b128 v[26:29], v143
	v_mfma_f32_16x16x32_bf16 v[58:61], v[6:9], v[106:109], v[58:61]
	ds_read_b128 v[22:25], v143 offset:1024
	v_mfma_f32_16x16x32_bf16 v[38:41], v[10:13], v[106:109], v[38:41]
	ds_read_b128 v[118:121], v127
	v_mfma_f32_16x16x32_bf16 v[30:33], v[14:17], v[106:109], v[30:33]
	ds_read_b128 v[114:117], v127 offset:1024
	ds_read_b128 v[110:113], v127 offset:2048
	ds_read_b128 v[106:109], v127 offset:3072
	v_mfma_f32_16x16x32_bf16 v[94:97], v[2:5], v[144:147], v[94:97]
	v_mfma_f32_16x16x32_bf16 v[82:85], v[6:9], v[144:147], v[82:85]
	v_mfma_f32_16x16x32_bf16 v[66:69], v[10:13], v[144:147], v[66:69]
	v_mfma_f32_16x16x32_bf16 v[34:37], v[14:17], v[144:147], v[34:37]
	s_waitcnt lgkmcnt(0)
	v_mfma_f32_16x16x32_bf16 v[102:105], v[118:121], v[26:29], v[102:105]
	v_mfma_f32_16x16x32_bf16 v[98:101], v[114:117], v[26:29], v[98:101]
	v_add_u32_e32 v132, s28, v142
	ds_read_b128 v[144:147], v132
	v_mfma_f32_16x16x32_bf16 v[86:89], v[110:113], v[26:29], v[86:89]
	ds_read_b128 v[122:125], v132 offset:1024
	v_mfma_f32_16x16x32_bf16 v[70:73], v[106:109], v[26:29], v[70:73]
	v_mfma_f32_16x16x32_bf16 v[90:93], v[118:121], v[22:25], v[90:93]
	v_mfma_f32_16x16x32_bf16 v[78:81], v[114:117], v[22:25], v[78:81]
	v_mfma_f32_16x16x32_bf16 v[62:65], v[110:113], v[22:25], v[62:65]
	v_mfma_f32_16x16x32_bf16 v[46:49], v[106:109], v[22:25], v[46:49]
	s_waitcnt vmcnt(0)
	s_waitcnt lgkmcnt(0)
	s_barrier
	v_mfma_f32_16x16x32_bf16 v[74:77], v[118:121], v[144:147], v[74:77]
	v_mfma_f32_16x16x32_bf16 v[58:61], v[114:117], v[144:147], v[58:61]
	v_mfma_f32_16x16x32_bf16 v[38:41], v[110:113], v[144:147], v[38:41]
	v_mfma_f32_16x16x32_bf16 v[30:33], v[106:109], v[144:147], v[30:33]
	s_add_u32 s20, s20, 0x80
	s_addc_u32 s21, s21, 0
	s_add_i32 s8, s8, 2
	s_cmp_gt_u32 s17, 29
	v_mfma_f32_16x16x32_bf16 v[94:97], v[118:121], v[122:125], v[94:97]
	v_mfma_f32_16x16x32_bf16 v[82:85], v[114:117], v[122:125], v[82:85]
	v_mfma_f32_16x16x32_bf16 v[66:69], v[110:113], v[122:125], v[66:69]
	v_mfma_f32_16x16x32_bf16 v[34:37], v[106:109], v[122:125], v[34:37]
	s_branch .LBB0_305

.Lgf_G1x_top:
	s_waitcnt vmcnt(4)
	s_waitcnt lgkmcnt(0)
	s_barrier
	v_mfma_f32_16x16x32_bf16 v[126:129], v[130:133], v[158:161], v[126:129]
	v_mfma_f32_16x16x32_bf16 v[98:101], v[134:137], v[158:161], v[98:101]
	s_add_i32 s28, s31, 0xfffe8000
	s_and_b32 s34, s28, 0x10000
	v_add_u32_e32 v170, s34, v233
	ds_read_b128 v[162:165], v170
	v_mfma_f32_16x16x32_bf16 v[66:69], v[138:141], v[158:161], v[66:69]
	ds_read_b128 v[166:169], v170 offset:1024
	v_mfma_f32_16x16x32_bf16 v[34:37], v[142:145], v[158:161], v[34:37]
	ds_read_b128 v[234:237], v170 offset:2048
	v_mfma_f32_16x16x32_bf16 v[122:125], v[130:133], v[154:157], v[122:125]
	ds_read_b128 v[238:241], v170 offset:3072
	s_and_b32 s40, s31, 0x18000
	s_add_i32 s40, s40, s69
	s_mov_b32 m0, s40
	v_mfma_f32_16x16x32_bf16 v[90:93], v[134:137], v[154:157], v[90:93]
	v_mfma_f32_16x16x32_bf16 v[58:61], v[138:141], v[154:157], v[58:61]
	global_load_lds_dwordx4 v188, s[94:95]
	s_add_i32 m0, s40, 0x2000
	v_mfma_f32_16x16x32_bf16 v[26:29], v[142:145], v[154:157], v[26:29]
	v_mfma_f32_16x16x32_bf16 v[118:121], v[130:133], v[150:153], v[118:121]
	v_mfma_f32_16x16x32_bf16 v[86:89], v[134:137], v[150:153], v[86:89]
	global_load_lds_dwordx4 v190, s[94:95]
	s_add_i32 m0, s40, 0x4000
	v_mfma_f32_16x16x32_bf16 v[54:57], v[138:141], v[150:153], v[54:57]
	v_mfma_f32_16x16x32_bf16 v[22:25], v[142:145], v[150:153], v[22:25]
	global_load_lds_dwordx4 v192, s[42:43]
	s_add_i32 m0, s40, 0x6000
	v_mfma_f32_16x16x32_bf16 v[114:117], v[130:133], v[146:149], v[114:117]
	v_mfma_f32_16x16x32_bf16 v[82:85], v[134:137], v[146:149], v[82:85]
	global_load_lds_dwordx4 v194, s[42:43]
	s_add_u32 s94, s94, 64
	s_addc_u32 s95, s95, 0
	s_add_u32 s42, s42, 64
	s_addc_u32 s43, s43, 0
	v_mfma_f32_16x16x32_bf16 v[50:53], v[138:141], v[146:149], v[50:53]
	v_mfma_f32_16x16x32_bf16 v[18:21], v[142:145], v[146:149], v[18:21]
	s_waitcnt lgkmcnt(0)
	v_mfma_f32_16x16x32_bf16 v[110:113], v[130:133], v[162:165], v[110:113]
	s_add_i32 s28, s31, 0xffff0000
	s_and_b32 s35, s28, 0x18000
	v_add_u32_e32 v189, s35, v231
	v_add_u32_e32 v226, s35, v232
	ds_read_b128 v[158:161], v226
	v_mfma_f32_16x16x32_bf16 v[78:81], v[134:137], v[162:165], v[78:81]
	ds_read_b128 v[154:157], v226 offset:1024
	v_mfma_f32_16x16x32_bf16 v[46:49], v[138:141], v[162:165], v[46:49]
	ds_read_b128 v[150:153], v226 offset:2048
	v_mfma_f32_16x16x32_bf16 v[14:17], v[142:145], v[162:165], v[14:17]
	ds_read_b128 v[146:149], v226 offset:3072
	v_mfma_f32_16x16x32_bf16 v[106:109], v[130:133], v[166:169], v[106:109]
	ds_read_b128 v[174:177], v189
	v_mfma_f32_16x16x32_bf16 v[74:77], v[134:137], v[166:169], v[74:77]
	ds_read_b128 v[170:173], v189 offset:1024
	v_mfma_f32_16x16x32_bf16 v[42:45], v[138:141], v[166:169], v[42:45]
	ds_read_b128 v[162:165], v189 offset:3072
	v_mfma_f32_16x16x32_bf16 v[10:13], v[142:145], v[166:169], v[10:13]
	ds_read_b128 v[166:169], v189 offset:2048
	v_mfma_f32_16x16x32_bf16 v[102:105], v[130:133], v[234:237], v[102:105]
	v_mfma_f32_16x16x32_bf16 v[70:73], v[134:137], v[234:237], v[70:73]
	v_mfma_f32_16x16x32_bf16 v[38:41], v[138:141], v[234:237], v[38:41]
	v_mfma_f32_16x16x32_bf16 v[6:9], v[142:145], v[234:237], v[6:9]
	v_mfma_f32_16x16x32_bf16 v[94:97], v[130:133], v[238:241], v[94:97]
	v_mfma_f32_16x16x32_bf16 v[62:65], v[134:137], v[238:241], v[62:65]
	v_mfma_f32_16x16x32_bf16 v[30:33], v[138:141], v[238:241], v[30:33]
	v_mfma_f32_16x16x32_bf16 v[2:5], v[142:145], v[238:241], v[2:5]
	s_waitcnt vmcnt(4)
	s_waitcnt lgkmcnt(0)
	s_barrier
	v_mfma_f32_16x16x32_bf16 v[126:129], v[174:177], v[158:161], v[126:129]
	v_mfma_f32_16x16x32_bf16 v[98:101], v[170:173], v[158:161], v[98:101]
	v_add_u32_e32 v226, s35, v233
	ds_read_b128 v[234:237], v226
	v_mfma_f32_16x16x32_bf16 v[66:69], v[166:169], v[158:161], v[66:69]
	ds_read_b128 v[238:241], v226 offset:1024
	v_mfma_f32_16x16x32_bf16 v[34:37], v[162:165], v[158:161], v[34:37]
	ds_read_b128 v[182:185], v226 offset:2048
	v_mfma_f32_16x16x32_bf16 v[122:125], v[174:177], v[154:157], v[122:125]
	ds_read_b128 v[178:181], v226 offset:3072
	s_add_i32 s40, s34, s69
	s_mov_b32 m0, s40
	v_mfma_f32_16x16x32_bf16 v[90:93], v[170:173], v[154:157], v[90:93]
	v_mfma_f32_16x16x32_bf16 v[58:61], v[166:169], v[154:157], v[58:61]
	global_load_lds_dwordx4 v188, s[94:95]
	s_add_i32 m0, s40, 0x2000
	v_mfma_f32_16x16x32_bf16 v[26:29], v[162:165], v[154:157], v[26:29]
	v_mfma_f32_16x16x32_bf16 v[118:121], v[174:177], v[150:153], v[118:121]
	v_mfma_f32_16x16x32_bf16 v[86:89], v[170:173], v[150:153], v[86:89]
	global_load_lds_dwordx4 v190, s[94:95]
	s_add_i32 m0, s40, 0x4000
	v_mfma_f32_16x16x32_bf16 v[54:57], v[166:169], v[150:153], v[54:57]
	v_mfma_f32_16x16x32_bf16 v[22:25], v[162:165], v[150:153], v[22:25]
	global_load_lds_dwordx4 v192, s[42:43]
	s_add_i32 m0, s40, 0x6000
	v_mfma_f32_16x16x32_bf16 v[114:117], v[174:177], v[146:149], v[114:117]
	v_mfma_f32_16x16x32_bf16 v[82:85], v[170:173], v[146:149], v[82:85]
	global_load_lds_dwordx4 v194, s[42:43]
	s_add_u32 s94, s94, 64
	s_addc_u32 s95, s95, 0
	s_add_u32 s42, s42, 64
	s_addc_u32 s43, s43, 0
	v_mfma_f32_16x16x32_bf16 v[50:53], v[166:169], v[146:149], v[50:53]
	v_mfma_f32_16x16x32_bf16 v[18:21], v[162:165], v[146:149], v[18:21]
	s_waitcnt lgkmcnt(0)
	v_mfma_f32_16x16x32_bf16 v[110:113], v[174:177], v[234:237], v[110:113]
	s_add_i32 s24, s31, 0xffff8000
	s_and_b32 s24, s24, 0x10000
	v_add_u32_e32 v189, s24, v231
	v_add_u32_e32 v226, s24, v232
	ds_read_b128 v[158:161], v226
	v_mfma_f32_16x16x32_bf16 v[78:81], v[170:173], v[234:237], v[78:81]
	ds_read_b128 v[154:157], v226 offset:1024
	v_mfma_f32_16x16x32_bf16 v[46:49], v[166:169], v[234:237], v[46:49]
	ds_read_b128 v[150:153], v226 offset:2048
	v_mfma_f32_16x16x32_bf16 v[14:17], v[162:165], v[234:237], v[14:17]
	ds_read_b128 v[146:149], v226 offset:3072
	v_mfma_f32_16x16x32_bf16 v[106:109], v[174:177], v[238:241], v[106:109]
	ds_read_b128 v[130:133], v189
	v_mfma_f32_16x16x32_bf16 v[74:77], v[170:173], v[238:241], v[74:77]
	ds_read_b128 v[134:137], v189 offset:1024
	v_mfma_f32_16x16x32_bf16 v[42:45], v[166:169], v[238:241], v[42:45]
	ds_read_b128 v[138:141], v189 offset:2048
	v_mfma_f32_16x16x32_bf16 v[10:13], v[162:165], v[238:241], v[10:13]
	ds_read_b128 v[142:145], v189 offset:3072
	s_add_i32 s30, s30, 2
	s_add_u32 s20, s20, 0x80
	s_addc_u32 s21, s21, 0
	s_add_i32 s31, s31, 0x10000
	v_mfma_f32_16x16x32_bf16 v[102:105], v[174:177], v[182:185], v[102:105]
	v_mfma_f32_16x16x32_bf16 v[70:73], v[170:173], v[182:185], v[70:73]
	v_mfma_f32_16x16x32_bf16 v[38:41], v[166:169], v[182:185], v[38:41]
	v_mfma_f32_16x16x32_bf16 v[6:9], v[162:165], v[182:185], v[6:9]
	v_mfma_f32_16x16x32_bf16 v[94:97], v[174:177], v[178:181], v[94:97]
	v_mfma_f32_16x16x32_bf16 v[62:65], v[170:173], v[178:181], v[62:65]
	v_mfma_f32_16x16x32_bf16 v[30:33], v[166:169], v[178:181], v[30:33]
	v_mfma_f32_16x16x32_bf16 v[2:5], v[162:165], v[178:181], v[2:5]
	s_cmp_lt_u32 s30, 28
	s_cbranch_scc1 .Lgf_G1x_top
	s_waitcnt vmcnt(4)
	s_waitcnt lgkmcnt(0)
	s_barrier
	v_mfma_f32_16x16x32_bf16 v[126:129], v[130:133], v[158:161], v[126:129]
	v_mfma_f32_16x16x32_bf16 v[98:101], v[134:137], v[158:161], v[98:101]
	s_add_i32 s28, s31, 0xfffe8000
	s_and_b32 s34, s28, 0x10000
	v_add_u32_e32 v170, s34, v233
	ds_read_b128 v[162:165], v170
	v_mfma_f32_16x16x32_bf16 v[66:69], v[138:141], v[158:161], v[66:69]
	ds_read_b128 v[166:169], v170 offset:1024
	v_mfma_f32_16x16x32_bf16 v[34:37], v[142:145], v[158:161], v[34:37]
	ds_read_b128 v[234:237], v170 offset:2048
	v_mfma_f32_16x16x32_bf16 v[122:125], v[130:133], v[154:157], v[122:125]
	ds_read_b128 v[238:241], v170 offset:3072
	s_and_b32 s40, s31, 0x18000
	s_add_i32 s40, s40, s69
	s_mov_b32 m0, s40
	v_mfma_f32_16x16x32_bf16 v[90:93], v[134:137], v[154:157], v[90:93]
	v_mfma_f32_16x16x32_bf16 v[58:61], v[138:141], v[154:157], v[58:61]
	global_load_lds_dwordx4 v188, s[94:95]
	s_add_i32 m0, s40, 0x2000
	v_mfma_f32_16x16x32_bf16 v[26:29], v[142:145], v[154:157], v[26:29]
	v_mfma_f32_16x16x32_bf16 v[118:121], v[130:133], v[150:153], v[118:121]
	v_mfma_f32_16x16x32_bf16 v[86:89], v[134:137], v[150:153], v[86:89]
	global_load_lds_dwordx4 v190, s[94:95]
	s_add_i32 m0, s40, 0x4000
	v_mfma_f32_16x16x32_bf16 v[54:57], v[138:141], v[150:153], v[54:57]
	v_mfma_f32_16x16x32_bf16 v[22:25], v[142:145], v[150:153], v[22:25]
	global_load_lds_dwordx4 v192, s[42:43]
	s_add_i32 m0, s40, 0x6000
	v_mfma_f32_16x16x32_bf16 v[114:117], v[130:133], v[146:149], v[114:117]
	v_mfma_f32_16x16x32_bf16 v[82:85], v[134:137], v[146:149], v[82:85]
	global_load_lds_dwordx4 v194, s[42:43]
	s_add_u32 s94, s94, 64
	s_addc_u32 s95, s95, 0
	s_add_u32 s42, s42, 64
	s_addc_u32 s43, s43, 0
	v_mfma_f32_16x16x32_bf16 v[50:53], v[138:141], v[146:149], v[50:53]
	v_mfma_f32_16x16x32_bf16 v[18:21], v[142:145], v[146:149], v[18:21]
	s_waitcnt lgkmcnt(0)
	v_mfma_f32_16x16x32_bf16 v[110:113], v[130:133], v[162:165], v[110:113]
	s_add_i32 s28, s31, 0xffff0000
	s_and_b32 s35, s28, 0x18000
	v_add_u32_e32 v189, s35, v231
	v_add_u32_e32 v226, s35, v232
	ds_read_b128 v[158:161], v226
	v_mfma_f32_16x16x32_bf16 v[78:81], v[134:137], v[162:165], v[78:81]
	ds_read_b128 v[154:157], v226 offset:1024
	v_mfma_f32_16x16x32_bf16 v[46:49], v[138:141], v[162:165], v[46:49]
	ds_read_b128 v[150:153], v226 offset:2048
	v_mfma_f32_16x16x32_bf16 v[14:17], v[142:145], v[162:165], v[14:17]
	ds_read_b128 v[146:149], v226 offset:3072
	v_mfma_f32_16x16x32_bf16 v[106:109], v[130:133], v[166:169], v[106:109]
	ds_read_b128 v[174:177], v189
	v_mfma_f32_16x16x32_bf16 v[74:77], v[134:137], v[166:169], v[74:77]
	ds_read_b128 v[170:173], v189 offset:1024
	v_mfma_f32_16x16x32_bf16 v[42:45], v[138:141], v[166:169], v[42:45]
	ds_read_b128 v[162:165], v189 offset:3072
	v_mfma_f32_16x16x32_bf16 v[10:13], v[142:145], v[166:169], v[10:13]
	ds_read_b128 v[166:169], v189 offset:2048
	v_mfma_f32_16x16x32_bf16 v[102:105], v[130:133], v[234:237], v[102:105]
	v_mfma_f32_16x16x32_bf16 v[70:73], v[134:137], v[234:237], v[70:73]
	v_mfma_f32_16x16x32_bf16 v[38:41], v[138:141], v[234:237], v[38:41]
	v_mfma_f32_16x16x32_bf16 v[6:9], v[142:145], v[234:237], v[6:9]
	v_mfma_f32_16x16x32_bf16 v[94:97], v[130:133], v[238:241], v[94:97]
	v_mfma_f32_16x16x32_bf16 v[62:65], v[134:137], v[238:241], v[62:65]
	v_mfma_f32_16x16x32_bf16 v[30:33], v[138:141], v[238:241], v[30:33]
	v_mfma_f32_16x16x32_bf16 v[2:5], v[142:145], v[238:241], v[2:5]
	s_waitcnt vmcnt(4)
	s_waitcnt lgkmcnt(0)
	s_barrier
	v_mfma_f32_16x16x32_bf16 v[126:129], v[174:177], v[158:161], v[126:129]
	v_mfma_f32_16x16x32_bf16 v[98:101], v[170:173], v[158:161], v[98:101]
	v_add_u32_e32 v226, s35, v233
	ds_read_b128 v[234:237], v226
	v_mfma_f32_16x16x32_bf16 v[66:69], v[166:169], v[158:161], v[66:69]
	ds_read_b128 v[238:241], v226 offset:1024
	v_mfma_f32_16x16x32_bf16 v[34:37], v[162:165], v[158:161], v[34:37]
	ds_read_b128 v[182:185], v226 offset:2048
	v_mfma_f32_16x16x32_bf16 v[122:125], v[174:177], v[154:157], v[122:125]
	ds_read_b128 v[178:181], v226 offset:3072
	v_mfma_f32_16x16x32_bf16 v[90:93], v[170:173], v[154:157], v[90:93]
	v_mfma_f32_16x16x32_bf16 v[58:61], v[166:169], v[154:157], v[58:61]
	v_mfma_f32_16x16x32_bf16 v[26:29], v[162:165], v[154:157], v[26:29]
	v_mfma_f32_16x16x32_bf16 v[118:121], v[174:177], v[150:153], v[118:121]
	v_mfma_f32_16x16x32_bf16 v[86:89], v[170:173], v[150:153], v[86:89]
	v_mfma_f32_16x16x32_bf16 v[54:57], v[166:169], v[150:153], v[54:57]
	v_mfma_f32_16x16x32_bf16 v[22:25], v[162:165], v[150:153], v[22:25]
	v_mfma_f32_16x16x32_bf16 v[114:117], v[174:177], v[146:149], v[114:117]
	v_mfma_f32_16x16x32_bf16 v[82:85], v[170:173], v[146:149], v[82:85]
	v_mfma_f32_16x16x32_bf16 v[50:53], v[166:169], v[146:149], v[50:53]
	v_mfma_f32_16x16x32_bf16 v[18:21], v[162:165], v[146:149], v[18:21]
	s_waitcnt lgkmcnt(0)
	v_mfma_f32_16x16x32_bf16 v[110:113], v[174:177], v[234:237], v[110:113]
	s_add_i32 s24, s31, 0xffff8000
	s_and_b32 s24, s24, 0x10000
	v_add_u32_e32 v189, s24, v231
	v_add_u32_e32 v226, s24, v232
	ds_read_b128 v[158:161], v226
	v_mfma_f32_16x16x32_bf16 v[78:81], v[170:173], v[234:237], v[78:81]
	ds_read_b128 v[154:157], v226 offset:1024
	v_mfma_f32_16x16x32_bf16 v[46:49], v[166:169], v[234:237], v[46:49]
	ds_read_b128 v[150:153], v226 offset:2048
	v_mfma_f32_16x16x32_bf16 v[14:17], v[162:165], v[234:237], v[14:17]
	ds_read_b128 v[146:149], v226 offset:3072
	v_mfma_f32_16x16x32_bf16 v[106:109], v[174:177], v[238:241], v[106:109]
	ds_read_b128 v[130:133], v189
	v_mfma_f32_16x16x32_bf16 v[74:77], v[170:173], v[238:241], v[74:77]
	ds_read_b128 v[134:137], v189 offset:1024
	v_mfma_f32_16x16x32_bf16 v[42:45], v[166:169], v[238:241], v[42:45]
	ds_read_b128 v[138:141], v189 offset:2048
	v_mfma_f32_16x16x32_bf16 v[10:13], v[162:165], v[238:241], v[10:13]
	ds_read_b128 v[142:145], v189 offset:3072
	s_add_i32 s30, s30, 2
	s_add_u32 s20, s20, 0x80
	s_addc_u32 s21, s21, 0
	s_add_i32 s31, s31, 0x10000
	v_mfma_f32_16x16x32_bf16 v[102:105], v[174:177], v[182:185], v[102:105]
	v_mfma_f32_16x16x32_bf16 v[70:73], v[170:173], v[182:185], v[70:73]
	v_mfma_f32_16x16x32_bf16 v[38:41], v[166:169], v[182:185], v[38:41]
	v_mfma_f32_16x16x32_bf16 v[6:9], v[162:165], v[182:185], v[6:9]
	v_mfma_f32_16x16x32_bf16 v[94:97], v[174:177], v[178:181], v[94:97]
	v_mfma_f32_16x16x32_bf16 v[62:65], v[170:173], v[178:181], v[62:65]
	v_mfma_f32_16x16x32_bf16 v[30:33], v[166:169], v[178:181], v[30:33]
	v_mfma_f32_16x16x32_bf16 v[2:5], v[162:165], v[178:181], v[2:5]
	s_waitcnt vmcnt(0)
	s_waitcnt lgkmcnt(0)
	s_barrier
	v_mfma_f32_16x16x32_bf16 v[126:129], v[130:133], v[158:161], v[126:129]
	v_mfma_f32_16x16x32_bf16 v[98:101], v[134:137], v[158:161], v[98:101]
	s_add_i32 s28, s31, 0xfffe8000
	s_and_b32 s34, s28, 0x10000
	v_add_u32_e32 v170, s34, v233
	ds_read_b128 v[162:165], v170
	v_mfma_f32_16x16x32_bf16 v[66:69], v[138:141], v[158:161], v[66:69]
	ds_read_b128 v[166:169], v170 offset:1024
	v_mfma_f32_16x16x32_bf16 v[34:37], v[142:145], v[158:161], v[34:37]
	ds_read_b128 v[234:237], v170 offset:2048
	v_mfma_f32_16x16x32_bf16 v[122:125], v[130:133], v[154:157], v[122:125]
	ds_read_b128 v[238:241], v170 offset:3072
	v_mfma_f32_16x16x32_bf16 v[90:93], v[134:137], v[154:157], v[90:93]
	v_mfma_f32_16x16x32_bf16 v[58:61], v[138:141], v[154:157], v[58:61]
	v_mfma_f32_16x16x32_bf16 v[26:29], v[142:145], v[154:157], v[26:29]
	v_mfma_f32_16x16x32_bf16 v[118:121], v[130:133], v[150:153], v[118:121]
	v_mfma_f32_16x16x32_bf16 v[86:89], v[134:137], v[150:153], v[86:89]
	v_mfma_f32_16x16x32_bf16 v[54:57], v[138:141], v[150:153], v[54:57]
	v_mfma_f32_16x16x32_bf16 v[22:25], v[142:145], v[150:153], v[22:25]
	v_mfma_f32_16x16x32_bf16 v[114:117], v[130:133], v[146:149], v[114:117]
	v_mfma_f32_16x16x32_bf16 v[82:85], v[134:137], v[146:149], v[82:85]
	v_mfma_f32_16x16x32_bf16 v[50:53], v[138:141], v[146:149], v[50:53]
	v_mfma_f32_16x16x32_bf16 v[18:21], v[142:145], v[146:149], v[18:21]
	s_waitcnt lgkmcnt(0)
	v_mfma_f32_16x16x32_bf16 v[110:113], v[130:133], v[162:165], v[110:113]
	s_add_i32 s28, s31, 0xffff0000
	s_and_b32 s35, s28, 0x18000
	v_add_u32_e32 v189, s35, v231
	v_add_u32_e32 v226, s35, v232
	ds_read_b128 v[158:161], v226
	v_mfma_f32_16x16x32_bf16 v[78:81], v[134:137], v[162:165], v[78:81]
	ds_read_b128 v[154:157], v226 offset:1024
	v_mfma_f32_16x16x32_bf16 v[46:49], v[138:141], v[162:165], v[46:49]
	ds_read_b128 v[150:153], v226 offset:2048
	v_mfma_f32_16x16x32_bf16 v[14:17], v[142:145], v[162:165], v[14:17]
	ds_read_b128 v[146:149], v226 offset:3072
	v_mfma_f32_16x16x32_bf16 v[106:109], v[130:133], v[166:169], v[106:109]
	ds_read_b128 v[174:177], v189
	v_mfma_f32_16x16x32_bf16 v[74:77], v[134:137], v[166:169], v[74:77]
	ds_read_b128 v[170:173], v189 offset:1024
	v_mfma_f32_16x16x32_bf16 v[42:45], v[138:141], v[166:169], v[42:45]
	ds_read_b128 v[162:165], v189 offset:3072
	v_mfma_f32_16x16x32_bf16 v[10:13], v[142:145], v[166:169], v[10:13]
	ds_read_b128 v[166:169], v189 offset:2048
	v_mfma_f32_16x16x32_bf16 v[102:105], v[130:133], v[234:237], v[102:105]
	v_mfma_f32_16x16x32_bf16 v[70:73], v[134:137], v[234:237], v[70:73]
	v_mfma_f32_16x16x32_bf16 v[38:41], v[138:141], v[234:237], v[38:41]
	v_mfma_f32_16x16x32_bf16 v[6:9], v[142:145], v[234:237], v[6:9]
	v_mfma_f32_16x16x32_bf16 v[94:97], v[130:133], v[238:241], v[94:97]
	v_mfma_f32_16x16x32_bf16 v[62:65], v[134:137], v[238:241], v[62:65]
	v_mfma_f32_16x16x32_bf16 v[30:33], v[138:141], v[238:241], v[30:33]
	v_mfma_f32_16x16x32_bf16 v[2:5], v[142:145], v[238:241], v[2:5]
	s_waitcnt vmcnt(0)
	s_waitcnt lgkmcnt(0)
	s_barrier
	v_mfma_f32_16x16x32_bf16 v[126:129], v[174:177], v[158:161], v[126:129]
	v_mfma_f32_16x16x32_bf16 v[98:101], v[170:173], v[158:161], v[98:101]
	v_add_u32_e32 v226, s35, v233
	ds_read_b128 v[234:237], v226
	v_mfma_f32_16x16x32_bf16 v[66:69], v[166:169], v[158:161], v[66:69]
	ds_read_b128 v[238:241], v226 offset:1024
	v_mfma_f32_16x16x32_bf16 v[34:37], v[162:165], v[158:161], v[34:37]
	ds_read_b128 v[182:185], v226 offset:2048
	v_mfma_f32_16x16x32_bf16 v[122:125], v[174:177], v[154:157], v[122:125]
	ds_read_b128 v[178:181], v226 offset:3072
	v_mfma_f32_16x16x32_bf16 v[90:93], v[170:173], v[154:157], v[90:93]
	v_mfma_f32_16x16x32_bf16 v[58:61], v[166:169], v[154:157], v[58:61]
	v_mfma_f32_16x16x32_bf16 v[26:29], v[162:165], v[154:157], v[26:29]
	v_mfma_f32_16x16x32_bf16 v[118:121], v[174:177], v[150:153], v[118:121]
	v_mfma_f32_16x16x32_bf16 v[86:89], v[170:173], v[150:153], v[86:89]
	v_mfma_f32_16x16x32_bf16 v[54:57], v[166:169], v[150:153], v[54:57]
	v_mfma_f32_16x16x32_bf16 v[22:25], v[162:165], v[150:153], v[22:25]
	v_mfma_f32_16x16x32_bf16 v[114:117], v[174:177], v[146:149], v[114:117]
	v_mfma_f32_16x16x32_bf16 v[82:85], v[170:173], v[146:149], v[82:85]
	v_mfma_f32_16x16x32_bf16 v[50:53], v[166:169], v[146:149], v[50:53]
	v_mfma_f32_16x16x32_bf16 v[18:21], v[162:165], v[146:149], v[18:21]
	s_waitcnt lgkmcnt(0)
	v_mfma_f32_16x16x32_bf16 v[110:113], v[174:177], v[234:237], v[110:113]
	v_mfma_f32_16x16x32_bf16 v[78:81], v[170:173], v[234:237], v[78:81]
	v_mfma_f32_16x16x32_bf16 v[46:49], v[166:169], v[234:237], v[46:49]
	v_mfma_f32_16x16x32_bf16 v[14:17], v[162:165], v[234:237], v[14:17]
	v_mfma_f32_16x16x32_bf16 v[106:109], v[174:177], v[238:241], v[106:109]
	v_mfma_f32_16x16x32_bf16 v[74:77], v[170:173], v[238:241], v[74:77]
	v_mfma_f32_16x16x32_bf16 v[42:45], v[166:169], v[238:241], v[42:45]
	v_mfma_f32_16x16x32_bf16 v[10:13], v[162:165], v[238:241], v[10:13]
	s_add_i32 s30, s30, 2
	s_add_u32 s20, s20, 0x80
	s_addc_u32 s21, s21, 0
	s_add_i32 s31, s31, 0x10000
	v_mfma_f32_16x16x32_bf16 v[102:105], v[174:177], v[182:185], v[102:105]
	v_mfma_f32_16x16x32_bf16 v[70:73], v[170:173], v[182:185], v[70:73]
	v_mfma_f32_16x16x32_bf16 v[38:41], v[166:169], v[182:185], v[38:41]
	v_mfma_f32_16x16x32_bf16 v[6:9], v[162:165], v[182:185], v[6:9]
	v_mfma_f32_16x16x32_bf16 v[94:97], v[174:177], v[178:181], v[94:97]
	v_mfma_f32_16x16x32_bf16 v[62:65], v[170:173], v[178:181], v[62:65]
	v_mfma_f32_16x16x32_bf16 v[30:33], v[166:169], v[178:181], v[30:33]
	v_mfma_f32_16x16x32_bf16 v[2:5], v[162:165], v[178:181], v[2:5]
	s_branch .LBB0_659

.Lgr_G1x_tail:
	s_waitcnt lgkmcnt(0)
	v_mfma_f32_16x16x32_bf16 v[126:129], v[130:133], v[158:161], v[126:129]
	v_mfma_f32_16x16x32_bf16 v[98:101], v[134:137], v[158:161], v[98:101]
	s_add_i32 s28, s31, 0xfffe8000
	s_and_b32 s34, s28, 0x10000
	v_add_u32_e32 v170, s34, v233
	ds_read_b128 v[162:165], v170
	v_mfma_f32_16x16x32_bf16 v[66:69], v[138:141], v[158:161], v[66:69]
	ds_read_b128 v[166:169], v170 offset:1024
	v_mfma_f32_16x16x32_bf16 v[34:37], v[142:145], v[158:161], v[34:37]
	ds_read_b128 v[234:237], v170 offset:2048
	v_mfma_f32_16x16x32_bf16 v[122:125], v[130:133], v[154:157], v[122:125]
	ds_read_b128 v[238:241], v170 offset:3072
	s_and_b32 s40, s31, 0x18000
	s_add_i32 s40, s40, s69
	s_mov_b32 m0, s40
	v_mfma_f32_16x16x32_bf16 v[90:93], v[134:137], v[154:157], v[90:93]
	v_mfma_f32_16x16x32_bf16 v[58:61], v[138:141], v[154:157], v[58:61]
	global_load_lds_dwordx4 v188, s[94:95]
	s_add_i32 m0, s40, 0x2000
	v_mfma_f32_16x16x32_bf16 v[26:29], v[142:145], v[154:157], v[26:29]
	v_mfma_f32_16x16x32_bf16 v[118:121], v[130:133], v[150:153], v[118:121]
	v_mfma_f32_16x16x32_bf16 v[86:89], v[134:137], v[150:153], v[86:89]
	global_load_lds_dwordx4 v190, s[94:95]
	s_add_i32 m0, s40, 0x4000
	v_mfma_f32_16x16x32_bf16 v[54:57], v[138:141], v[150:153], v[54:57]
	v_mfma_f32_16x16x32_bf16 v[22:25], v[142:145], v[150:153], v[22:25]
	global_load_lds_dwordx4 v192, s[42:43]
	s_add_i32 m0, s40, 0x6000
	v_mfma_f32_16x16x32_bf16 v[114:117], v[130:133], v[146:149], v[114:117]
	v_mfma_f32_16x16x32_bf16 v[82:85], v[134:137], v[146:149], v[82:85]
	global_load_lds_dwordx4 v194, s[42:43]
	s_add_u32 s94, s94, 64
	s_addc_u32 s95, s95, 0
	s_add_u32 s42, s42, 64
	s_addc_u32 s43, s43, 0
	v_mfma_f32_16x16x32_bf16 v[50:53], v[138:141], v[146:149], v[50:53]
	v_mfma_f32_16x16x32_bf16 v[18:21], v[142:145], v[146:149], v[18:21]
	s_waitcnt vmcnt(4)
	s_waitcnt lgkmcnt(0)
	s_barrier
	v_mfma_f32_16x16x32_bf16 v[110:113], v[130:133], v[162:165], v[110:113]
	s_add_i32 s28, s31, 0xffff0000
	s_and_b32 s35, s28, 0x18000
	v_add_u32_e32 v189, s35, v231
	v_add_u32_e32 v226, s35, v232
	ds_read_b128 v[158:161], v226
	v_mfma_f32_16x16x32_bf16 v[78:81], v[134:137], v[162:165], v[78:81]
	ds_read_b128 v[154:157], v226 offset:1024
	v_mfma_f32_16x16x32_bf16 v[46:49], v[138:141], v[162:165], v[46:49]
	ds_read_b128 v[150:153], v226 offset:2048
	v_mfma_f32_16x16x32_bf16 v[14:17], v[142:145], v[162:165], v[14:17]
	ds_read_b128 v[146:149], v226 offset:3072
	v_mfma_f32_16x16x32_bf16 v[106:109], v[130:133], v[166:169], v[106:109]
	ds_read_b128 v[174:177], v189
	v_mfma_f32_16x16x32_bf16 v[74:77], v[134:137], v[166:169], v[74:77]
	ds_read_b128 v[170:173], v189 offset:1024
	v_mfma_f32_16x16x32_bf16 v[42:45], v[138:141], v[166:169], v[42:45]
	ds_read_b128 v[162:165], v189 offset:3072
	v_mfma_f32_16x16x32_bf16 v[10:13], v[142:145], v[166:169], v[10:13]
	ds_read_b128 v[166:169], v189 offset:2048
	v_mfma_f32_16x16x32_bf16 v[102:105], v[130:133], v[234:237], v[102:105]
	v_mfma_f32_16x16x32_bf16 v[70:73], v[134:137], v[234:237], v[70:73]
	v_mfma_f32_16x16x32_bf16 v[38:41], v[138:141], v[234:237], v[38:41]
	v_mfma_f32_16x16x32_bf16 v[6:9], v[142:145], v[234:237], v[6:9]
	v_mfma_f32_16x16x32_bf16 v[94:97], v[130:133], v[238:241], v[94:97]
	v_mfma_f32_16x16x32_bf16 v[62:65], v[134:137], v[238:241], v[62:65]
	v_mfma_f32_16x16x32_bf16 v[30:33], v[138:141], v[238:241], v[30:33]
	v_mfma_f32_16x16x32_bf16 v[2:5], v[142:145], v[238:241], v[2:5]
	s_waitcnt lgkmcnt(0)
	v_mfma_f32_16x16x32_bf16 v[126:129], v[174:177], v[158:161], v[126:129]
	v_mfma_f32_16x16x32_bf16 v[98:101], v[170:173], v[158:161], v[98:101]
	v_add_u32_e32 v226, s35, v233
	ds_read_b128 v[234:237], v226
	v_mfma_f32_16x16x32_bf16 v[66:69], v[166:169], v[158:161], v[66:69]
	ds_read_b128 v[238:241], v226 offset:1024
	v_mfma_f32_16x16x32_bf16 v[34:37], v[162:165], v[158:161], v[34:37]
	ds_read_b128 v[182:185], v226 offset:2048
	v_mfma_f32_16x16x32_bf16 v[122:125], v[174:177], v[154:157], v[122:125]
	ds_read_b128 v[178:181], v226 offset:3072
	v_mfma_f32_16x16x32_bf16 v[90:93], v[170:173], v[154:157], v[90:93]
	v_mfma_f32_16x16x32_bf16 v[58:61], v[166:169], v[154:157], v[58:61]
	v_mfma_f32_16x16x32_bf16 v[26:29], v[162:165], v[154:157], v[26:29]
	v_mfma_f32_16x16x32_bf16 v[118:121], v[174:177], v[150:153], v[118:121]
	v_mfma_f32_16x16x32_bf16 v[86:89], v[170:173], v[150:153], v[86:89]
	v_mfma_f32_16x16x32_bf16 v[54:57], v[166:169], v[150:153], v[54:57]
	v_mfma_f32_16x16x32_bf16 v[22:25], v[162:165], v[150:153], v[22:25]
	v_mfma_f32_16x16x32_bf16 v[114:117], v[174:177], v[146:149], v[114:117]
	v_mfma_f32_16x16x32_bf16 v[82:85], v[170:173], v[146:149], v[82:85]
	v_mfma_f32_16x16x32_bf16 v[50:53], v[166:169], v[146:149], v[50:53]
	v_mfma_f32_16x16x32_bf16 v[18:21], v[162:165], v[146:149], v[18:21]
	s_waitcnt vmcnt(0)
	s_waitcnt lgkmcnt(0)
	s_barrier
	v_mfma_f32_16x16x32_bf16 v[110:113], v[174:177], v[234:237], v[110:113]
	s_add_i32 s24, s31, 0xffff8000
	s_and_b32 s24, s24, 0x10000
	v_add_u32_e32 v189, s24, v231
	v_add_u32_e32 v226, s24, v232
	ds_read_b128 v[158:161], v226
	v_mfma_f32_16x16x32_bf16 v[78:81], v[170:173], v[234:237], v[78:81]
	ds_read_b128 v[154:157], v226 offset:1024
	v_mfma_f32_16x16x32_bf16 v[46:49], v[166:169], v[234:237], v[46:49]
	ds_read_b128 v[150:153], v226 offset:2048
	v_mfma_f32_16x16x32_bf16 v[14:17], v[162:165], v[234:237], v[14:17]
	ds_read_b128 v[146:149], v226 offset:3072
	v_mfma_f32_16x16x32_bf16 v[106:109], v[174:177], v[238:241], v[106:109]
	ds_read_b128 v[130:133], v189
	v_mfma_f32_16x16x32_bf16 v[74:77], v[170:173], v[238:241], v[74:77]
	ds_read_b128 v[134:137], v189 offset:1024
	v_mfma_f32_16x16x32_bf16 v[42:45], v[166:169], v[238:241], v[42:45]
	ds_read_b128 v[138:141], v189 offset:2048
	v_mfma_f32_16x16x32_bf16 v[10:13], v[162:165], v[238:241], v[10:13]
	ds_read_b128 v[142:145], v189 offset:3072
	s_add_i32 s30, s30, 2
	s_add_u32 s20, s20, 0x80
	s_addc_u32 s21, s21, 0
	s_add_i32 s31, s31, 0x10000
	v_mfma_f32_16x16x32_bf16 v[102:105], v[174:177], v[182:185], v[102:105]
	v_mfma_f32_16x16x32_bf16 v[70:73], v[170:173], v[182:185], v[70:73]
	v_mfma_f32_16x16x32_bf16 v[38:41], v[166:169], v[182:185], v[38:41]
	v_mfma_f32_16x16x32_bf16 v[6:9], v[162:165], v[182:185], v[6:9]
	v_mfma_f32_16x16x32_bf16 v[94:97], v[174:177], v[178:181], v[94:97]
	v_mfma_f32_16x16x32_bf16 v[62:65], v[170:173], v[178:181], v[62:65]
	v_mfma_f32_16x16x32_bf16 v[30:33], v[166:169], v[178:181], v[30:33]
	v_mfma_f32_16x16x32_bf16 v[2:5], v[162:165], v[178:181], v[2:5]
	s_waitcnt lgkmcnt(0)
	v_mfma_f32_16x16x32_bf16 v[126:129], v[130:133], v[158:161], v[126:129]
	v_mfma_f32_16x16x32_bf16 v[98:101], v[134:137], v[158:161], v[98:101]
	s_add_i32 s28, s31, 0xfffe8000
	s_and_b32 s34, s28, 0x10000
	v_add_u32_e32 v170, s34, v233
	ds_read_b128 v[162:165], v170
	v_mfma_f32_16x16x32_bf16 v[66:69], v[138:141], v[158:161], v[66:69]
	ds_read_b128 v[166:169], v170 offset:1024
	v_mfma_f32_16x16x32_bf16 v[34:37], v[142:145], v[158:161], v[34:37]
	ds_read_b128 v[234:237], v170 offset:2048
	v_mfma_f32_16x16x32_bf16 v[122:125], v[130:133], v[154:157], v[122:125]
	ds_read_b128 v[238:241], v170 offset:3072
	v_mfma_f32_16x16x32_bf16 v[90:93], v[134:137], v[154:157], v[90:93]
	v_mfma_f32_16x16x32_bf16 v[58:61], v[138:141], v[154:157], v[58:61]
	v_mfma_f32_16x16x32_bf16 v[26:29], v[142:145], v[154:157], v[26:29]
	v_mfma_f32_16x16x32_bf16 v[118:121], v[130:133], v[150:153], v[118:121]
	v_mfma_f32_16x16x32_bf16 v[86:89], v[134:137], v[150:153], v[86:89]
	v_mfma_f32_16x16x32_bf16 v[54:57], v[138:141], v[150:153], v[54:57]
	v_mfma_f32_16x16x32_bf16 v[22:25], v[142:145], v[150:153], v[22:25]
	v_mfma_f32_16x16x32_bf16 v[114:117], v[130:133], v[146:149], v[114:117]
	v_mfma_f32_16x16x32_bf16 v[82:85], v[134:137], v[146:149], v[82:85]
	v_mfma_f32_16x16x32_bf16 v[50:53], v[138:141], v[146:149], v[50:53]
	v_mfma_f32_16x16x32_bf16 v[18:21], v[142:145], v[146:149], v[18:21]
	s_waitcnt vmcnt(0)
	s_waitcnt lgkmcnt(0)
	s_barrier
	v_mfma_f32_16x16x32_bf16 v[110:113], v[130:133], v[162:165], v[110:113]
	s_add_i32 s28, s31, 0xffff0000
	s_and_b32 s35, s28, 0x18000
	v_add_u32_e32 v189, s35, v231
	v_add_u32_e32 v226, s35, v232
	ds_read_b128 v[158:161], v226
	v_mfma_f32_16x16x32_bf16 v[78:81], v[134:137], v[162:165], v[78:81]
	ds_read_b128 v[154:157], v226 offset:1024
	v_mfma_f32_16x16x32_bf16 v[46:49], v[138:141], v[162:165], v[46:49]
	ds_read_b128 v[150:153], v226 offset:2048
	v_mfma_f32_16x16x32_bf16 v[14:17], v[142:145], v[162:165], v[14:17]
	ds_read_b128 v[146:149], v226 offset:3072
	v_mfma_f32_16x16x32_bf16 v[106:109], v[130:133], v[166:169], v[106:109]
	ds_read_b128 v[174:177], v189
	v_mfma_f32_16x16x32_bf16 v[74:77], v[134:137], v[166:169], v[74:77]
	ds_read_b128 v[170:173], v189 offset:1024
	v_mfma_f32_16x16x32_bf16 v[42:45], v[138:141], v[166:169], v[42:45]
	ds_read_b128 v[162:165], v189 offset:3072
	v_mfma_f32_16x16x32_bf16 v[10:13], v[142:145], v[166:169], v[10:13]
	ds_read_b128 v[166:169], v189 offset:2048
	v_mfma_f32_16x16x32_bf16 v[102:105], v[130:133], v[234:237], v[102:105]
	v_mfma_f32_16x16x32_bf16 v[70:73], v[134:137], v[234:237], v[70:73]
	v_mfma_f32_16x16x32_bf16 v[38:41], v[138:141], v[234:237], v[38:41]
	v_mfma_f32_16x16x32_bf16 v[6:9], v[142:145], v[234:237], v[6:9]
	v_mfma_f32_16x16x32_bf16 v[94:97], v[130:133], v[238:241], v[94:97]
	v_mfma_f32_16x16x32_bf16 v[62:65], v[134:137], v[238:241], v[62:65]
	v_mfma_f32_16x16x32_bf16 v[30:33], v[138:141], v[238:241], v[30:33]
	v_mfma_f32_16x16x32_bf16 v[2:5], v[142:145], v[238:241], v[2:5]
	s_waitcnt lgkmcnt(0)
	v_mfma_f32_16x16x32_bf16 v[126:129], v[174:177], v[158:161], v[126:129]
	v_mfma_f32_16x16x32_bf16 v[98:101], v[170:173], v[158:161], v[98:101]
	v_add_u32_e32 v226, s35, v233
	ds_read_b128 v[234:237], v226
	v_mfma_f32_16x16x32_bf16 v[66:69], v[166:169], v[158:161], v[66:69]
	ds_read_b128 v[238:241], v226 offset:1024
	v_mfma_f32_16x16x32_bf16 v[34:37], v[162:165], v[158:161], v[34:37]
	ds_read_b128 v[182:185], v226 offset:2048
	v_mfma_f32_16x16x32_bf16 v[122:125], v[174:177], v[154:157], v[122:125]
	ds_read_b128 v[178:181], v226 offset:3072
	v_mfma_f32_16x16x32_bf16 v[90:93], v[170:173], v[154:157], v[90:93]
	v_mfma_f32_16x16x32_bf16 v[58:61], v[166:169], v[154:157], v[58:61]
	v_mfma_f32_16x16x32_bf16 v[26:29], v[162:165], v[154:157], v[26:29]
	v_mfma_f32_16x16x32_bf16 v[118:121], v[174:177], v[150:153], v[118:121]
	v_mfma_f32_16x16x32_bf16 v[86:89], v[170:173], v[150:153], v[86:89]
	v_mfma_f32_16x16x32_bf16 v[54:57], v[166:169], v[150:153], v[54:57]
	v_mfma_f32_16x16x32_bf16 v[22:25], v[162:165], v[150:153], v[22:25]
	v_mfma_f32_16x16x32_bf16 v[114:117], v[174:177], v[146:149], v[114:117]
	v_mfma_f32_16x16x32_bf16 v[82:85], v[170:173], v[146:149], v[82:85]
	v_mfma_f32_16x16x32_bf16 v[50:53], v[166:169], v[146:149], v[50:53]
	v_mfma_f32_16x16x32_bf16 v[18:21], v[162:165], v[146:149], v[18:21]
	s_waitcnt vmcnt(0)
	s_waitcnt lgkmcnt(0)
	s_barrier
	v_mfma_f32_16x16x32_bf16 v[110:113], v[174:177], v[234:237], v[110:113]
	v_mfma_f32_16x16x32_bf16 v[78:81], v[170:173], v[234:237], v[78:81]
	v_mfma_f32_16x16x32_bf16 v[46:49], v[166:169], v[234:237], v[46:49]
	v_mfma_f32_16x16x32_bf16 v[14:17], v[162:165], v[234:237], v[14:17]
	v_mfma_f32_16x16x32_bf16 v[106:109], v[174:177], v[238:241], v[106:109]
	v_mfma_f32_16x16x32_bf16 v[74:77], v[170:173], v[238:241], v[74:77]
	v_mfma_f32_16x16x32_bf16 v[42:45], v[166:169], v[238:241], v[42:45]
	v_mfma_f32_16x16x32_bf16 v[10:13], v[162:165], v[238:241], v[10:13]
	s_add_i32 s30, s30, 2
	s_add_u32 s20, s20, 0x80
	s_addc_u32 s21, s21, 0
	s_add_i32 s31, s31, 0x10000
	v_mfma_f32_16x16x32_bf16 v[102:105], v[174:177], v[182:185], v[102:105]
	v_mfma_f32_16x16x32_bf16 v[70:73], v[170:173], v[182:185], v[70:73]
	v_mfma_f32_16x16x32_bf16 v[38:41], v[166:169], v[182:185], v[38:41]
	v_mfma_f32_16x16x32_bf16 v[6:9], v[162:165], v[182:185], v[6:9]
	v_mfma_f32_16x16x32_bf16 v[94:97], v[174:177], v[178:181], v[94:97]
	v_mfma_f32_16x16x32_bf16 v[62:65], v[170:173], v[178:181], v[62:65]
	v_mfma_f32_16x16x32_bf16 v[30:33], v[166:169], v[178:181], v[30:33]
	v_mfma_f32_16x16x32_bf16 v[2:5], v[162:165], v[178:181], v[2:5]
	s_branch .LBB0_659
